# attention K/V prefetch addressing moved to SGPR bases advanced by SALU (removes ten 64-bit VALU address ops per loop iteration in the MLA and diff loops)
# speedup vs baseline: 1.0543x; 1.0091x over previous
; DI float shx(float v, int k) { return __int_as_float(__builtin_amdgcn_ds_bpermute((lane_id_l() ^ k) << 2, __float_as_int(v))); }
; DI int get_tid() { int t = threadIdx.x; asm volatile("" : "+v"(t)); return t; }
; DI void diff_attn_item(const Params& P, const WsPtrs& W, int layer, int item, unsigned char* smem) {
;   const int w = get_tid() >> 6, lane = get_tid() & 63, r = lane & 31, h = lane >> 5;
;   int bh = item >> 5, qb = item & 31, bl = bh >> 3, hh = bh & 7;
;   int sub = w >> 2;
;   int q0 = qb * 128 + 32 * (w & 3);
;   size_t tokb = (size_t)bl * 4096;
;   f32x16 o[4]; float l;
;   float gq = fabsf(P.in[I_DQG][layer * 64 + lane]), gk = fabsf(P.in[I_DKG][layer * 64 + lane]);
; #pragma unroll
;   for (int of = 32; of > 0; of >>= 1) { gq = fmaxf(gq, shx(gq, of)); gk = fmaxf(gk, shx(gk, of)); }
;   const float M = 11.5416f * gq * gk * 1.02f + 1.f;
;   if (M <= 56.f)
;     attn_core<128, 64, 1>(W.Y + (tokb + q0) * LDY + O_BQ + hh * 128 + sub * 64, LDY, W.Y + tokb * LDY + O_BK + hh * 128, LDY,
;                           W.BVT + (size_t)bh * 128 * 4096, sub * 64, q0, M, o, l, smem);
;   else
;     attn_core<128, 64, 0>(W.Y + (tokb + q0) * LDY + O_BQ + hh * 128 + sub * 64, LDY, W.Y + tokb * LDY + O_BK + hh * 128, LDY,
;                           W.BVT + (size_t)bh * 128 * 4096, sub * 64, q0, 0.f, o, l, smem);
.LBB0_558:
	v_readlane_b32 s2, v253, 10
	s_mov_b32 s8, s2
	v_mov_b32_e32 v161, v250
	s_waitcnt vmcnt(1)
	v_mov_b32_e32 v162, v250
	v_readlane_b32 s6, v255, 17
	v_and_b32_e32 v163, 63, v162
	v_readlane_b32 s20, v254, 49
	v_or_b32_e32 v0, s6, v163
	v_lshlrev_b64 v[2:3], 2, v[0:1]
	v_readlane_b32 s21, v254, 50
	v_readlane_b32 s22, v254, 51
	v_readlane_b32 s23, v254, 52
	v_lshl_add_u64 v[4:5], s[20:21], 0, v[2:3]
	global_load_dword v0, v[4:5], off
	v_lshl_add_u64 v[2:3], s[22:23], 0, v[2:3]
	global_load_dword v2, v[2:3], off
	v_mov_b32_e32 v3, v229
	v_mov_b32_e32 v4, v229
	v_mov_b32_e32 v5, v229
	v_lshlrev_b32_e32 v3, 2, v3
	v_lshlrev_b32_e32 v4, 2, v4
	v_xor_b32_e32 v3, 0x80, v3
	v_xor_b32_e32 v4, 0x80, v4
	v_mov_b32_e32 v6, v229
	v_mov_b32_e32 v7, v229
	v_lshlrev_b32_e32 v5, 2, v5
	v_lshlrev_b32_e32 v6, 2, v6
	v_xor_b32_e32 v5, 64, v5
	v_xor_b32_e32 v6, 64, v6
	v_mov_b32_e32 v8, v229
	v_mov_b32_e32 v9, v229
	v_lshlrev_b32_e32 v7, 2, v7
	v_lshlrev_b32_e32 v8, 2, v8
	v_xor_b32_e32 v7, 32, v7
	v_xor_b32_e32 v8, 32, v8
	v_mov_b32_e32 v10, v229
	v_mov_b32_e32 v11, v229
	v_lshlrev_b32_e32 v9, 2, v9
	v_lshlrev_b32_e32 v10, 2, v10
	v_xor_b32_e32 v9, 16, v9
	v_xor_b32_e32 v10, 16, v10
	v_mov_b32_e32 v12, v229
	v_mov_b32_e32 v13, v229
	v_lshlrev_b32_e32 v11, 2, v11
	v_lshlrev_b32_e32 v12, 2, v12
	v_xor_b32_e32 v11, 8, v11
	v_xor_b32_e32 v12, 8, v12
	v_mov_b32_e32 v14, v229
	s_ashr_i32 s9, s8, 31
	s_lshl_b64 s[10:11], s[8:9], 14
	v_lshlrev_b32_e32 v13, 2, v13
	s_add_u32 s22, s10, 0x7046100
	v_lshlrev_b32_e32 v14, 2, v14
	v_xor_b32_e32 v13, 4, v13
	s_addc_u32 s23, s11, 0
	v_xor_b32_e32 v14, 4, v14
	v_readlane_b32 s7, v255, 18
	s_add_u32 s12, s62, s22
	s_mul_i32 s21, s8, 0x6600000
	s_addc_u32 s13, s63, s23
	s_lshl_b64 s[6:7], s[8:9], 24
	s_mul_hi_i32 s20, s8, 0x6600000
	s_add_u32 s2, s12, s21
	v_readlane_b32 s26, v254, 55
	s_addc_u32 s14, s13, s20
	v_readlane_b32 s27, v254, 56
	s_add_u32 s26, s2, s6
	s_addc_u32 s27, s14, s7
	s_lshr_b32 s2, s19, 2
	s_bfe_i32 s14, s19, 0x180005
	s_lshl_b32 s6, s19, 7
	v_bfe_u32 v164, v161, 6, 2
	s_and_b32 s19, s2, 0x7fffff8
	s_ashr_i32 s15, s14, 31
	s_and_b32 s2, s6, 0xf80
	v_lshl_or_b32 v168, v164, 5, s2
	s_lshl_b64 s[6:7], s[14:15], 12
	s_mov_b32 s2, 0x3f828f5c
	v_readlane_b32 s24, v254, 53
	v_readlane_b32 s25, v254, 54
	v_ashrrev_i32_e32 v165, 8, v161
	s_waitcnt vmcnt(1)
	v_and_b32_e32 v15, 0x7fffffff, v0
	ds_bpermute_b32 v3, v3, v15
	s_waitcnt vmcnt(0)
	v_and_b32_e32 v16, 0x7fffffff, v2
	ds_bpermute_b32 v4, v4, v16
	v_max_f32_e64 v0, |v0|, |v0|
	v_max_f32_e64 v2, |v2|, |v2|
	s_waitcnt lgkmcnt(1)
	v_max_f32_e32 v3, v3, v3
	v_max_f32_e32 v0, v0, v3
	s_waitcnt lgkmcnt(0)
	v_max_f32_e32 v4, v4, v4
	v_max_f32_e32 v4, v2, v4
	ds_bpermute_b32 v5, v5, v0
	ds_bpermute_b32 v6, v6, v4
	v_mov_b64_e32 v[2:3], s[12:13]
	v_lshlrev_b32_e32 v146, 6, v165
	v_ashrrev_i32_e32 v147, 31, v146
	s_waitcnt lgkmcnt(1)
	v_max_f32_e32 v5, v5, v5
	s_waitcnt lgkmcnt(0)
	v_max_f32_e32 v6, v6, v6
	v_max_f32_e32 v0, v0, v5
	v_max_f32_e32 v4, v4, v6
	ds_bpermute_b32 v5, v7, v0
	ds_bpermute_b32 v6, v8, v4
	v_or_b32_e32 v7, s6, v168
	v_mad_u64_u32 v[2:3], s[24:25], v7, s33, v[2:3]
	s_waitcnt lgkmcnt(1)
	v_max_f32_e32 v5, v5, v5
	s_waitcnt lgkmcnt(0)
	v_max_f32_e32 v6, v6, v6
	v_max_f32_e32 v0, v0, v5
	v_max_f32_e32 v4, v4, v6
	ds_bpermute_b32 v5, v9, v0
	ds_bpermute_b32 v6, v10, v4
	s_or_b32 s16, s19, s81
	s_mov_b64 s[24:25], 0x1000
	s_bfe_i32 s16, s16, 0x1b0000
	s_waitcnt lgkmcnt(1)
	v_max_f32_e32 v5, v5, v5
	s_waitcnt lgkmcnt(0)
	v_max_f32_e32 v6, v6, v6
	v_max_f32_e32 v0, v0, v5
	v_max_f32_e32 v4, v4, v6
	ds_bpermute_b32 v5, v11, v0
	ds_bpermute_b32 v6, v12, v4
	s_waitcnt lgkmcnt(1)
	v_max_f32_e32 v5, v5, v5
	s_waitcnt lgkmcnt(0)
	v_max_f32_e32 v6, v6, v6
	v_max_f32_e32 v0, v0, v5
	v_max_f32_e32 v4, v4, v6
	ds_bpermute_b32 v5, v13, v0
	ds_bpermute_b32 v6, v14, v4
	s_waitcnt lgkmcnt(1)
	v_max_f32_e32 v5, v5, v5
	s_waitcnt lgkmcnt(0)
	v_max_f32_e32 v6, v6, v6
	v_max_f32_e32 v0, v0, v5
	v_max_f32_e32 v4, v4, v6
	v_mul_f32_e32 v0, 0x4138aa65, v0
	v_mul_f32_e32 v0, v0, v4
	v_fma_f32 v0, v0, s2, 1.0
	s_mov_b32 s2, 0x42600000
	v_cmp_ge_f32_e32 vcc, s2, v0
	v_mov_b32_e32 v4, 0x6600
	v_readlane_b32 s2, v255, 41
	v_mad_i32_i24 v3, s7, v4, v3
	s_lshl_b32 s2, s2, 1
	v_lshl_add_u64 v[2:3], v[2:3], 0, s[2:3]
	v_lshl_add_u64 v[2:3], v[146:147], 1, v[2:3]
	v_lshl_add_u64 v[82:83], v[2:3], 0, s[24:25]
	s_mul_i32 s25, s14, 0x6600000
	s_mul_hi_i32 s24, s14, 0x6600000
	s_add_u32 s12, s12, s25
	s_addc_u32 s13, s13, s24
	s_add_u32 s12, s12, s2
	s_addc_u32 s13, s13, 0
	s_add_u32 s12, s12, 0x1800
	s_addc_u32 s13, s13, 0
	s_ashr_i32 s17, s16, 31
	s_lshl_b64 s[14:15], s[16:17], 20
	s_add_u32 s14, s26, s14
	s_addc_u32 s15, s27, s15
	s_mul_hi_i32 s26, s8, 0x7604000
	s_mul_i32 s27, s8, 0x7604000
	s_and_saveexec_b64 s[16:17], vcc
	s_xor_b64 s[16:17], exec, s[16:17]
	s_cbranch_execz .LBB0_567
; DI int get_tid() { int t = threadIdx.x; asm volatile("" : "+v"(t)); return t; }
;     ...
;   const int tid = get_tid(), lane = tid & 63, r = lane & 31, h = lane >> 5;
;   bf16x8 qf[NQ];
; #pragma unroll
;   for (int ks = 0; ks < NQ; ++ks) qf[ks] = qpre ? qpre[ks] : *(const bf16x8*)(Qw + (size_t)r * ldq + 16 * ks + 8 * h);
;   if (zero_o) {
; #pragma unroll
;     for (int dt = 0; dt < 4; ++dt)
; #pragma unroll
;       for (int e = 0; e < 16; ++e) o[dt][e] = 0.f;
;   }
;   float m_run = -1e30f, l_run = 0.f;
;   u32x4 rk[NKL], rv[2];
;   u32 koff[NKL]; int klds[NKL];
; #pragma unroll
;   for (int i = 0; i < NKL; ++i) { int c = tid + NTHR * i; int row = c / KCH, kc = c % KCH; koff[i] = (u32)(row * ldk + 8 * kc) * 2u; klds[i] = row * KST + 8 * kc; }
;   const u32 voff = (u32)((tid >> 3) * 4096 + 8 * (tid & 7)) * 2u;
;   const int vlds = 64 * KST + (tid >> 3) * 72 + 8 * (tid & 7);
;   auto gload = [&](int k0) __attribute__((always_inline)) {
;     const char* kb = (const char*)Kg + (size_t)k0 * ldk * 2;
; #pragma unroll
;     for (int i = 0; i < NKL; ++i) rk[i] = *(const u32x4*)(kb + koff[i]);
;     const char* vb = (const char*)VTg + (size_t)k0 * 2;
; #pragma unroll
;     for (int i = 0; i < 2; ++i) rv[i] = *(const u32x4*)(vb + (size_t)i * 64 * 4096 * 2 + voff);
;   };
;   auto lstore = [&](int b) __attribute__((always_inline)) {
;     u16* St = S0 + b * STG;
; #pragma unroll
;     for (int i = 0; i < NKL; ++i) *(u32x4*)(St + klds[i]) = rk[i];
; #pragma unroll
;     for (int i = 0; i < 2; ++i) *(u32x4*)(St + vlds + i * 64 * 72) = rv[i];
;   };
;   gload(kt0 * 64);
;   __syncthreads();
;   lstore(0);
;   gload((kt0 + 1) * 64);
;   __syncthreads();
;   const float qpos = (float)(qpos0 + r);
	v_mov_b32_e32 v19, v250
	v_xor_b32_e32 v66, 0x80000000, v0
	v_ashrrev_i32_e32 v2, 31, v19
	v_lshrrev_b32_e32 v2, 28, v2
	v_add_u32_e32 v2, v19, v2
	v_ashrrev_i32_e32 v23, 4, v2
	v_and_b32_e32 v2, 0x1ffffff0, v2
	v_sub_u32_e32 v2, v19, v2
	v_mul_lo_u32 v3, v23, s56
	v_lshl_add_u32 v18, v2, 3, v3
	v_add_u32_e32 v2, 0x200, v19
	v_ashrrev_i32_e32 v3, 31, v2
	v_lshrrev_b32_e32 v3, 28, v3
	v_add_u32_e32 v3, v2, v3
	v_ashrrev_i32_e32 v32, 4, v3
	v_and_b32_e32 v3, 0x1ffffff0, v3
	v_sub_u32_e32 v2, v2, v3
	v_mul_lo_u32 v3, v32, s56
	v_lshl_add_u32 v22, v2, 3, v3
	v_ashrrev_i32_e32 v27, 3, v19
	v_lshlrev_b32_e32 v2, 3, v19
	v_and_b32_e32 v33, 31, v19
	v_and_b32_e32 v26, 56, v2
	v_lshlrev_b32_e32 v2, 13, v27
	v_lshrrev_b32_e32 v0, 2, v19
	v_mul_u32_u24_e32 v19, 0x3300, v33
	v_lshl_or_b32 v28, v26, 1, v2
	v_mov_b32_e32 v29, v1
	v_and_b32_e32 v34, 8, v0
	v_lshlrev_b32_e32 v0, 1, v19
	s_movk_i32 s71, 0x48
	v_lshl_add_u64 v[10:11], s[14:15], 0, v[28:29]
	s_mov_b32 s70, 0x80000
	s_add_u32 s74, s12, 0x198000
	v_mad_u64_u32 v[148:149], s[84:85], v27, s71, v[26:27]
	v_lshl_add_u64 v[26:27], v[82:83], 0, v[0:1]
	v_lshlrev_b32_e32 v0, 1, v34
	v_lshlrev_b32_e32 v20, 1, v18
	v_add_co_u32_e32 v30, vcc, s70, v10
	s_addc_u32 s75, s13, 0
	v_lshl_add_u64 v[26:27], v[26:27], 0, v[0:1]
	v_lshlrev_b32_e32 v24, 1, v22
	global_load_dwordx4 v[2:5], v20, s[12:13]
	global_load_dwordx4 v[6:9], v24, s[12:13]
	v_addc_co_u32_e32 v31, vcc, 0, v11, vcc
	global_load_dwordx4 v[10:13], v28, s[14:15]
	global_load_dwordx4 v[14:17], v[30:31], off
	global_load_dwordx4 v[114:117], v[26:27], off
	global_load_dwordx4 v[118:121], v[26:27], off offset:32
	global_load_dwordx4 v[122:125], v[26:27], off offset:64
	global_load_dwordx4 v[126:129], v[26:27], off offset:96
	s_barrier
	global_load_dwordx4 v[130:133], v20, s[74:75]
	global_load_dwordx4 v[134:137], v24, s[74:75]
	global_load_dwordx4 v[138:141], v28, s[14:15] offset:128
	global_load_dwordx4 v[142:145], v[30:31], off offset:128
	v_lshl_add_u32 v19, v148, 1, 64
	s_movk_i32 s71, 0xcd88
	v_mad_u64_u32 v[150:151], s[84:85], v23, s71, v[18:19]
	v_mad_u64_u32 v[152:153], s[84:85], v32, s71, v[22:23]
	v_readlane_b32 s71, v255, 25
	s_or_b32 s71, s71, s19
	s_bfe_i32 s75, s71, 0x1001a
	s_bfe_i32 s74, s71, 0x1b0000
	s_lshl_b64 s[74:75], s[74:75], 20
	s_add_u32 s74, s27, s74
	s_addc_u32 s75, s26, s75
	v_readlane_b32 s71, v255, 44
	v_mov_b32_e32 v154, v28
	v_add_u32_e32 v155, 0x80000, v28
	s_add_u32 s100, s74, s62
	s_addc_u32 s101, s75, s63
	s_add_u32 s100, s100, 0x7046000
	s_addc_u32 s101, s101, 0
	s_add_u32 s71, s71, s25
	v_readlane_b32 s74, v255, 45
	s_addc_u32 s75, s74, s24
	v_lshl_add_u32 v18, v150, 1, 64
	s_add_u32 s74, s71, s10
	v_mov_b32_e32 v21, v1
	v_mov_b32_e32 v25, v1
	v_lshl_add_u32 v22, v152, 1, 64
	s_addc_u32 s75, s75, s11
	v_mov_b32_e32 v147, 0
	s_mov_b32 s70, 0
	v_mov_b32_e32 v67, v66
	v_mov_b32_e32 v68, v66
	v_mov_b32_e32 v69, v66
	v_mov_b32_e32 v70, v66
	v_mov_b32_e32 v71, v66
	v_mov_b32_e32 v72, v66
	v_mov_b32_e32 v73, v66
	v_mov_b32_e32 v74, v66
	v_mov_b32_e32 v75, v66
	v_mov_b32_e32 v76, v66
	v_mov_b32_e32 v77, v66
	v_mov_b32_e32 v78, v66
	v_mov_b32_e32 v79, v66
	v_mov_b32_e32 v80, v66
	v_mov_b32_e32 v81, v66
	v_mul_u32_u24_e32 v149, 0x110, v33
	v_mov_b32_e32 v156, v20
	s_waitcnt vmcnt(11)
	ds_write_b128 v18, v[2:5]
	s_waitcnt vmcnt(10)
	ds_write_b128 v22, v[6:9]
	s_waitcnt vmcnt(9)
	ds_write_b128 v19, v[10:13] offset:17408
	s_waitcnt vmcnt(8)
	ds_write_b128 v19, v[14:17] offset:26624
	v_mul_u32_u24_e32 v2, 0x48, v33
	v_mov_b32_e32 v157, v24
	s_add_u32 s74, s74, s62
	s_addc_u32 s75, s75, s63
	v_lshlrev_b32_e32 v151, 1, v2
	v_mov_b32_e32 v18, 0
	v_mov_b32_e32 v19, v147
	v_mov_b32_e32 v20, v147
	v_mov_b32_e32 v21, v147
	v_mov_b32_e32 v22, v147
	v_mov_b32_e32 v23, v147
	v_mov_b32_e32 v24, v147
	v_mov_b32_e32 v25, v147
	v_mov_b32_e32 v26, v147
	v_mov_b32_e32 v27, v147
	v_mov_b32_e32 v28, v147
	v_mov_b32_e32 v29, v147
	v_mov_b32_e32 v30, v147
	v_mov_b32_e32 v31, v147
	v_mov_b32_e32 v32, v147
	v_mov_b32_e32 v33, v147
	v_mov_b32_e32 v34, 0
	v_mov_b32_e32 v35, v147
	v_mov_b32_e32 v36, v147
	v_mov_b32_e32 v37, v147
	v_mov_b32_e32 v38, v147
	v_mov_b32_e32 v39, v147
	v_mov_b32_e32 v40, v147
	v_mov_b32_e32 v41, v147
	v_mov_b32_e32 v42, v147
	v_mov_b32_e32 v43, v147
	v_mov_b32_e32 v44, v147
	v_mov_b32_e32 v45, v147
	v_mov_b32_e32 v46, v147
	v_mov_b32_e32 v47, v147
	v_mov_b32_e32 v48, v147
	v_mov_b32_e32 v49, v147
	v_mov_b32_e32 v50, 0
	v_mov_b32_e32 v51, v147
	v_mov_b32_e32 v52, v147
	v_mov_b32_e32 v53, v147
	v_mov_b32_e32 v54, v147
	v_mov_b32_e32 v55, v147
	v_mov_b32_e32 v56, v147
	v_mov_b32_e32 v57, v147
	v_mov_b32_e32 v58, v147
	v_mov_b32_e32 v59, v147
	v_mov_b32_e32 v60, v147
	v_mov_b32_e32 v61, v147
	v_mov_b32_e32 v62, v147
	v_mov_b32_e32 v63, v147
	v_mov_b32_e32 v64, v147
	v_mov_b32_e32 v65, v147
	v_mov_b32_e32 v2, 0
	v_mov_b32_e32 v3, v147
	v_mov_b32_e32 v4, v147
	v_mov_b32_e32 v5, v147
	v_mov_b32_e32 v6, v147
	v_mov_b32_e32 v7, v147
	v_mov_b32_e32 v8, v147
	v_mov_b32_e32 v9, v147
	v_mov_b32_e32 v10, v147
	v_mov_b32_e32 v11, v147
	v_mov_b32_e32 v12, v147
	v_mov_b32_e32 v13, v147
	v_mov_b32_e32 v14, v147
	v_mov_b32_e32 v15, v147
	v_mov_b32_e32 v16, v147
	v_mov_b32_e32 v17, v147
	s_waitcnt lgkmcnt(0)
	s_barrier
	v_mov_b32_e32 v170, 0
	v_mov_b32_e32 v171, 0
	v_mov_b32_e32 v172, 0
	v_mov_b32_e32 v173, 0
	v_mov_b32_e32 v174, 0
	v_mov_b32_e32 v175, 0
	v_mov_b32_e32 v176, 0
	v_mov_b32_e32 v177, 0
	v_mov_b32_e32 v178, 0
	v_mov_b32_e32 v179, 0
	v_mov_b32_e32 v180, 0
	v_mov_b32_e32 v181, 0
	v_mov_b32_e32 v182, 0
	v_mov_b32_e32 v183, 0
	v_mov_b32_e32 v184, 0
	v_mov_b32_e32 v185, 0
	v_mov_b32_e32 v246, 0
	v_mov_b32_e32 v247, 0
	v_mov_b32_e32 v248, 0
	v_mov_b32_e32 v249, 0
	v_mov_b32_e32 v82, 0
	v_mov_b32_e32 v83, 0
	v_mov_b32_e32 v84, 0
	v_mov_b32_e32 v85, 0
	v_mov_b32_e32 v86, 0
	v_mov_b32_e32 v87, 0
	v_mov_b32_e32 v88, 0
	v_mov_b32_e32 v89, 0
	v_mov_b32_e32 v90, 0
	v_mov_b32_e32 v91, 0
	v_mov_b32_e32 v92, 0
	v_mov_b32_e32 v93, 0
	v_mov_b32_e32 v94, 0
	v_mov_b32_e32 v95, 0
	v_mov_b32_e32 v96, 0
	v_mov_b32_e32 v97, 0
.LBB0_560:
	s_bitcmp1_b32 s70, 0
	s_cselect_b32 s71, 0x8c00, 0
	s_add_i32 s71, s71, 64
	v_add_u32_e32 v160, s71, v149
	v_lshlrev_b32_e32 v166, 1, v146
	v_add3_u32 v160, v160, v166, v0
	v_add3_u32 v153, s71, v0, v151
	ds_read_b128 v[186:189], v160
	ds_read_b128 v[190:193], v160 offset:32
	ds_read_b128 v[194:197], v160 offset:64
	ds_read_b128 v[198:201], v160 offset:96
	s_add_i32 s71, s70, 1
	s_bitcmp1_b32 s71, 0
	s_cselect_b32 vcc_lo, 0x8c00, 0
	s_add_i32 vcc_lo, vcc_lo, 64
	v_mfma_f32_32x32x16_bf16 v[2:17], v[170:173], v[246:249], v[2:17]
	ds_read_b128 v[170:173], v160 offset:8704
	v_lshl_add_u32 v202, v150, 1, vcc_lo
	v_lshl_add_u32 v203, v152, 1, vcc_lo
	v_lshl_add_u32 v204, v148, 1, vcc_lo
	v_add_f32_e32 v166, v82, v83
	v_mfma_f32_32x32x16_bf16 v[50:65], v[174:177], v[246:249], v[50:65]
	ds_read_b128 v[174:177], v160 offset:8736
	s_waitcnt vmcnt(0)
	v_add_f32_e32 v166, v84, v166
	v_add_f32_e32 v166, v85, v166
	v_add_f32_e32 v166, v86, v166
	v_add_f32_e32 v166, v87, v166
	s_waitcnt lgkmcnt(5)
	v_mfma_f32_32x32x16_bf16 v[98:113], v[186:189], v[114:117], v[66:81]
	ds_read_b128 v[186:189], v153 offset:17408
	ds_write_b128 v202, v[130:133]
	ds_write_b128 v203, v[134:137]
	v_add_f32_e32 v166, v88, v166
	v_add_f32_e32 v166, v89, v166
	s_waitcnt lgkmcnt(7)
	v_mfma_f32_32x32x16_bf16 v[98:113], v[190:193], v[118:121], v[98:113]
	ds_read_b128 v[190:193], v153 offset:22016
	ds_write_b128 v204, v[138:141] offset:17408
	ds_write_b128 v204, v[142:145] offset:26624
	v_add_f32_e32 v166, v90, v166
	v_add_f32_e32 v166, v91, v166
	s_waitcnt lgkmcnt(9)
	v_mfma_f32_32x32x16_bf16 v[98:113], v[194:197], v[122:125], v[98:113]
	ds_read_b128 v[194:197], v153 offset:26624
	s_waitcnt lgkmcnt(9)
	v_mfma_f32_32x32x16_bf16 v[98:113], v[198:201], v[126:129], v[98:113]
	ds_read_b128 v[198:201], v153 offset:31232
	s_cmp_gt_u32 s70, 61
	s_cbranch_scc1 .Ldiff_skip_gb
	global_load_dwordx4 v[130:133], v156, s[74:75]
	global_load_dwordx4 v[134:137], v157, s[74:75]
	global_load_dwordx4 v[138:141], v154, s[100:101] offset:512
	global_load_dwordx4 v[142:145], v155, s[100:101] offset:512
.Ldiff_skip_gb:
	s_add_u32 s74, s74, s90
	s_addc_u32 s75, s75, s91
	s_add_u32 s100, s100, s30
	s_addc_u32 s101, s101, s31
	v_mfma_f32_32x32x16_bf16 v[34:49], v[178:181], v[246:249], v[34:49]
	ds_read_b128 v[178:181], v160 offset:8768
	v_add_f32_e32 v166, v92, v166
	v_add_f32_e32 v166, v93, v166
	v_mfma_f32_32x32x16_bf16 v[18:33], v[182:185], v[246:249], v[18:33]
	ds_read_b128 v[182:185], v160 offset:8800
	v_add_f32_e32 v166, v94, v166
	v_add_f32_e32 v166, v95, v166
	v_add_f32_e32 v166, v96, v166
	v_add_f32_e32 v166, v97, v166
	v_add_f32_e32 v147, v147, v166
	s_waitcnt lgkmcnt(11)
	v_mfma_f32_32x32x16_bf16 v[82:97], v[170:173], v[114:117], v[66:81]
	v_exp_f32_e32 v98, v98
	v_exp_f32_e32 v99, v99
	v_exp_f32_e32 v100, v100
	s_waitcnt lgkmcnt(10)
	v_mfma_f32_32x32x16_bf16 v[82:97], v[174:177], v[118:121], v[82:97]
	ds_read_b128 v[170:173], v153 offset:17440
	v_exp_f32_e32 v101, v101
	v_exp_f32_e32 v102, v102
	v_exp_f32_e32 v103, v103
	s_waitcnt lgkmcnt(2)
	v_mfma_f32_32x32x16_bf16 v[82:97], v[178:181], v[122:125], v[82:97]
	ds_read_b128 v[174:177], v153 offset:22048
	v_exp_f32_e32 v104, v104
	v_exp_f32_e32 v105, v105
	v_cvt_pk_bf16_f32 v202, v98, v99
	v_cvt_pk_bf16_f32 v203, v100, v101
	v_cvt_pk_bf16_f32 v204, v102, v103
	v_cvt_pk_bf16_f32 v205, v104, v105
	s_waitcnt lgkmcnt(2)
	v_mfma_f32_32x32x16_bf16 v[82:97], v[182:185], v[126:129], v[82:97]
	ds_read_b128 v[178:181], v153 offset:26656
	v_exp_f32_e32 v106, v106
	v_exp_f32_e32 v107, v107
	v_exp_f32_e32 v108, v108
	v_mfma_f32_32x32x16_bf16 v[2:17], v[186:189], v[202:205], v[2:17]
	ds_read_b128 v[182:185], v153 offset:31264
	ds_read_b128 v[186:189], v153 offset:17472
	v_exp_f32_e32 v109, v109
	v_exp_f32_e32 v110, v110
	v_exp_f32_e32 v111, v111
	v_mfma_f32_32x32x16_bf16 v[50:65], v[190:193], v[202:205], v[50:65]
	ds_read_b128 v[190:193], v153 offset:22080
	v_exp_f32_e32 v112, v112
	v_exp_f32_e32 v113, v113
	v_add_f32_e32 v160, v98, v99
	v_add_f32_e32 v160, v100, v160
	v_mfma_f32_32x32x16_bf16 v[34:49], v[194:197], v[202:205], v[34:49]
	ds_read_b128 v[194:197], v153 offset:26688
	v_cvt_pk_bf16_f32 v246, v106, v107
	v_cvt_pk_bf16_f32 v247, v108, v109
	v_cvt_pk_bf16_f32 v248, v110, v111
	v_cvt_pk_bf16_f32 v249, v112, v113
	v_add_f32_e32 v160, v101, v160
	v_add_f32_e32 v160, v102, v160
	v_mfma_f32_32x32x16_bf16 v[18:33], v[198:201], v[202:205], v[18:33]
	ds_read_b128 v[198:201], v153 offset:31296
	v_exp_f32_e32 v82, v82
	v_exp_f32_e32 v83, v83
	v_exp_f32_e32 v84, v84
	s_waitcnt lgkmcnt(7)
	v_mfma_f32_32x32x16_bf16 v[2:17], v[170:173], v[246:249], v[2:17]
	ds_read_b128 v[170:173], v153 offset:17504
	v_exp_f32_e32 v85, v85
	v_exp_f32_e32 v86, v86
	v_exp_f32_e32 v87, v87
	s_waitcnt lgkmcnt(7)
	v_mfma_f32_32x32x16_bf16 v[50:65], v[174:177], v[246:249], v[50:65]
	ds_read_b128 v[174:177], v153 offset:22112
	v_exp_f32_e32 v88, v88
	v_exp_f32_e32 v89, v89
	v_cvt_pk_bf16_f32 v202, v82, v83
	v_add_f32_e32 v160, v103, v160
	s_waitcnt lgkmcnt(7)
	v_mfma_f32_32x32x16_bf16 v[34:49], v[178:181], v[246:249], v[34:49]
	ds_read_b128 v[178:181], v153 offset:26720
	v_cvt_pk_bf16_f32 v203, v84, v85
	v_cvt_pk_bf16_f32 v204, v86, v87
	v_cvt_pk_bf16_f32 v205, v88, v89
	v_exp_f32_e32 v90, v90
	v_add_f32_e32 v160, v104, v160
	s_waitcnt lgkmcnt(7)
	v_mfma_f32_32x32x16_bf16 v[18:33], v[182:185], v[246:249], v[18:33]
	ds_read_b128 v[182:185], v153 offset:31328
	v_exp_f32_e32 v91, v91
	v_exp_f32_e32 v92, v92
	v_exp_f32_e32 v93, v93
	s_waitcnt lgkmcnt(7)
	v_mfma_f32_32x32x16_bf16 v[2:17], v[186:189], v[202:205], v[2:17]
	v_exp_f32_e32 v94, v94
	v_exp_f32_e32 v95, v95
	v_exp_f32_e32 v96, v96
	s_waitcnt lgkmcnt(6)
	v_mfma_f32_32x32x16_bf16 v[50:65], v[190:193], v[202:205], v[50:65]
	v_exp_f32_e32 v97, v97
	v_add_f32_e32 v160, v105, v160
	v_add_f32_e32 v160, v106, v160
	v_add_f32_e32 v160, v107, v160
	v_add_f32_e32 v160, v108, v160
	v_add_f32_e32 v160, v109, v160
	s_waitcnt lgkmcnt(5)
	v_mfma_f32_32x32x16_bf16 v[34:49], v[194:197], v[202:205], v[34:49]
	v_cvt_pk_bf16_f32 v246, v90, v91
	v_cvt_pk_bf16_f32 v247, v92, v93
	v_cvt_pk_bf16_f32 v248, v94, v95
	v_cvt_pk_bf16_f32 v249, v96, v97
	v_add_f32_e32 v160, v110, v160
	v_add_f32_e32 v160, v111, v160
	s_waitcnt lgkmcnt(4)
	v_mfma_f32_32x32x16_bf16 v[18:33], v[198:201], v[202:205], v[18:33]
	v_add_f32_e32 v160, v112, v160
	v_add_f32_e32 v160, v113, v160
	v_add_f32_e32 v147, v147, v160
	s_cmp_lg_u32 s71, 64
	s_waitcnt lgkmcnt(0)
	s_mov_b32 s70, s71
	s_barrier
	s_cbranch_scc1 .LBB0_560

; DI float bflo(u32 v) { return __uint_as_float(v << 16); }
; DI float bfhi(u32 v) { return __uint_as_float(v & 0xffff0000u); }
; DI float shx(float v, int k) { return __int_as_float(__builtin_amdgcn_ds_bpermute((lane_id_l() ^ k) << 2, __float_as_int(v))); }
; DI int get_tid() { int t = threadIdx.x; asm volatile("" : "+v"(t)); return t; }
; DI void mla_attn_item(const WsPtrs& W, const float* pgq, const float* pgk, int item, unsigned char* smem) {
;   const int w = get_tid() >> 6, lane = get_tid() & 63, r = lane & 31, h = lane >> 5;
;   int bh = item >> 4, qb = item & 15, bl = bh >> 3, hh = bh & 7;
;   int q0 = qb * 256 + 32 * w;
;   size_t tokb = (size_t)bl * 4096;
;   f32x16 o[4]; float l;
;   float gq = 0.f, gk = 0.f;
;   for (int i = lane; i < 192; i += 64) { gq = fmaxf(gq, fabsf(pgq[i])); gk = fmaxf(gk, fabsf(pgk[i])); }
; #pragma unroll
;   for (int of = 32; of > 0; of >>= 1) { gq = fmaxf(gq, shx(gq, of)); gk = fmaxf(gk, shx(gk, of)); }
;   const float M = 19.99f * gq * gk * 1.02f + 1.f;
;   bf16x8 qn[12];
;   {
;     const u16* Qr = W.QC + (tokb + q0 + r) * 1536 + hh * 192 + 8 * h;
;     u32x4 raw[12];
; #pragma unroll
;     for (int ks = 0; ks < 12; ++ks) raw[ks] = *(const u32x4*)(Qr + 16 * ks);
;     float ss = 0.f;
; #pragma unroll
;     for (int ks = 0; ks < 12; ++ks) {
;       float a;
;       a = bflo(raw[ks].x); ss += a * a; a = bfhi(raw[ks].x); ss += a * a; a = bflo(raw[ks].y); ss += a * a; a = bfhi(raw[ks].y); ss += a * a;
;       a = bflo(raw[ks].z); ss += a * a; a = bfhi(raw[ks].z); ss += a * a; a = bflo(raw[ks].w); ss += a * a; a = bfhi(raw[ks].w); ss += a * a;
;     }
;     ss += shx(ss, 32);
;     const float sc = rsqrtf(ss * (1.f / 192.f) + EPSV) * (0.07216878364870322f * LOG2E);
;     const float pos = (float)(q0 + r);
;     auto scaled = [&](int ks, float (&v)[8]) __attribute__((always_inline)) {
;       const f32x4 g0 = *(const f32x4*)(pgq + 16 * ks + 8 * h), g1 = *(const f32x4*)(pgq + 16 * ks + 8 * h + 4);
.LBB0_587:
	global_load_dword v11, v[2:3], off
	v_max_f32_e32 v0, v0, v0
	v_add_u32_e32 v10, 64, v10
	s_movk_i32 s2, 0x7f
	v_max_f32_e32 v8, v8, v8
	v_cmp_lt_u32_e32 vcc, s2, v10
	v_lshl_add_u64 v[2:3], v[2:3], 0, s[76:77]
	s_or_b64 s[6:7], vcc, s[6:7]
	s_waitcnt vmcnt(0)
	v_max_f32_e64 v11, |v11|, |v11|
	v_max_f32_e32 v0, v0, v11
	global_load_dword v11, v[4:5], off
	v_lshl_add_u64 v[4:5], v[4:5], 0, s[76:77]
	s_waitcnt vmcnt(0)
	v_max_f32_e64 v11, |v11|, |v11|
	v_max_f32_e32 v8, v8, v11
	s_andn2_b64 exec, exec, s[6:7]
	s_cbranch_execnz .LBB0_587
	s_or_b64 exec, exec, s[6:7]
	v_readlane_b32 s2, v254, 28
	s_ashr_i32 s5, s4, 31
	s_sub_i32 s16, s18, s2
	s_lshl_b64 s[6:7], s[4:5], 23
	s_lshl_b64 s[8:9], s[4:5], 25
	s_mul_i32 s5, s4, 0x6604000
	s_mul_hi_i32 s2, s4, 0x6604000
	s_add_u32 s5, s8, s5
	s_addc_u32 s2, s9, s2
	s_add_u32 s5, s5, 0x7046100
	s_addc_u32 s14, s2, 0
	s_add_u32 s6, s5, s6
	s_addc_u32 s7, s14, s7
	s_add_u32 s8, s62, s6
	v_mov_b32_e32 v3, v229
	s_mul_i32 s10, s4, 0xc00000
	s_addc_u32 s9, s63, s7
	v_mov_b32_e32 v4, v229
	s_mul_hi_i32 s2, s4, 0xc00000
	s_add_u32 s11, s8, s10
	v_lshlrev_b32_e32 v3, 2, v3
	s_addc_u32 s12, s9, s2
	s_lshr_b32 s6, s16, 1
	v_xor_b32_e32 v3, 0x80, v3
	v_lshlrev_b32_e32 v4, 2, v4
	s_and_b32 s13, s6, 0xffffff8
	ds_bpermute_b32 v3, v3, v0
	v_xor_b32_e32 v4, 0x80, v4
	s_or_b32 s15, s13, s81
	s_bfe_i32 s6, s16, 0x190004
	ds_bpermute_b32 v4, v4, v8
	s_add_u32 s5, s62, s5
	v_ashrrev_i32_e32 v2, 1, v9
	s_addc_u32 s14, s63, s14
	s_lshl_b32 s16, s16, 8
	v_and_b32_e32 v2, 0xffffffe0, v2
	s_and_b32 s16, s16, 0xf00
	v_add_u32_e32 v10, s16, v2
	s_waitcnt lgkmcnt(1)
	v_max_f32_e32 v2, v3, v3
	v_max_f32_e32 v0, v0, v0
	v_max_f32_e32 v9, v0, v2
	s_waitcnt lgkmcnt(0)
	v_max_f32_e32 v0, v4, v4
	v_max_f32_e32 v2, v8, v8
	v_max_f32_e32 v8, v2, v0
	v_mov_b32_e32 v0, v229
	s_ashr_i32 s7, s6, 31
	v_lshlrev_b32_e32 v0, 2, v0
	v_xor_b32_e32 v0, 64, v0
	s_lshl_b64 s[16:17], s[6:7], 12
	v_ashrrev_i32_e32 v11, 31, v10
	ds_bpermute_b32 v12, v0, v9
	v_mov_b32_e32 v0, v229
	v_and_b32_e32 v22, 31, v7
	v_lshl_add_u64 v[182:183], s[16:17], 0, v[10:11]
	v_or_b32_e32 v182, v182, v22
	v_mov_b64_e32 v[2:3], s[8:9]
	s_movk_i32 s7, 0xc00
	v_readlane_b32 s20, v255, 23
	v_lshlrev_b32_e32 v0, 2, v0
	v_mad_u64_u32 v[2:3], s[8:9], v182, s7, v[2:3]
	v_readlane_b32 s21, v255, 24
	v_lshrrev_b32_e32 v223, 5, v6
	v_xor_b32_e32 v0, 64, v0
	v_mad_i32_i24 v3, v183, s7, v3
	s_mov_b32 s21, s3
	ds_bpermute_b32 v13, v0, v8
	v_lshl_add_u64 v[2:3], v[2:3], 0, s[20:21]
	v_lshlrev_b32_e32 v0, 4, v223
	v_readlane_b32 s8, v253, 54
	v_mov_b32_e32 v14, v229
	v_mov_b32_e32 v15, v229
	v_mov_b32_e32 v16, v229
	v_mov_b32_e32 v17, v229
	v_mov_b32_e32 v18, v229
	v_mov_b32_e32 v19, v229
	v_mov_b32_e32 v20, v229
	v_mov_b32_e32 v21, v229
	v_lshl_add_u64 v[2:3], v[2:3], 0, v[0:1]
	v_mov_b32_e32 v11, v229
	v_and_b32_e32 v154, 32, v6
	v_readlane_b32 s9, v253, 55
	global_load_dwordx4 v[98:101], v[2:3], off
	global_load_dwordx4 v[106:109], v[2:3], off offset:32
	global_load_dwordx4 v[110:113], v[2:3], off offset:64
	global_load_dwordx4 v[114:117], v[2:3], off offset:96
	global_load_dwordx4 v[118:121], v[2:3], off offset:128
	global_load_dwordx4 v[122:125], v[2:3], off offset:160
	global_load_dwordx4 v[126:129], v[2:3], off offset:192
	global_load_dwordx4 v[130:133], v[2:3], off offset:224
	global_load_dwordx4 v[138:141], v[2:3], off offset:256
	global_load_dwordx4 v[146:149], v[2:3], off offset:288
	global_load_dwordx4 v[134:137], v[2:3], off offset:320
	global_load_dwordx4 v[142:145], v[2:3], off offset:352
	global_load_dwordx4 v[2:5], v154, s[8:9] offset:32
	s_waitcnt lgkmcnt(0)
	v_max_f32_e32 v6, v13, v13
	v_max_f32_e32 v0, v12, v12
	v_max_f32_e32 v12, v8, v6
	v_lshlrev_b32_e32 v6, 2, v14
	v_max_f32_e32 v0, v9, v0
	v_xor_b32_e32 v6, 32, v6
	ds_bpermute_b32 v13, v6, v0
	v_lshlrev_b32_e32 v6, 2, v15
	v_xor_b32_e32 v6, 32, v6
	ds_bpermute_b32 v14, v6, v12
	global_load_dwordx4 v[6:9], v154, s[8:9] offset:48
	global_load_dwordx4 v[168:171], v154, s[8:9] offset:96
	global_load_dwordx4 v[102:105], v154, s[8:9] offset:112
	s_waitcnt lgkmcnt(1)
	v_max_f32_e32 v13, v13, v13
	v_max_f32_e32 v0, v0, v13
	s_waitcnt lgkmcnt(0)
	v_max_f32_e32 v13, v14, v14
	v_or_b32_e32 v10, v10, v22
	v_max_f32_e32 v12, v12, v13
	v_lshlrev_b32_e32 v13, 2, v16
	v_cvt_f32_i32_e32 v224, v10
	v_xor_b32_e32 v13, 16, v13
	v_lshlrev_b32_e32 v14, 2, v17
	ds_bpermute_b32 v13, v13, v0
	v_xor_b32_e32 v14, 16, v14
	ds_bpermute_b32 v14, v14, v12
	v_lshlrev_b32_e32 v11, 2, v11
	v_xor_b32_e32 v155, 0x80, v11
	s_waitcnt lgkmcnt(1)
	v_max_f32_e32 v13, v13, v13
	v_max_f32_e32 v0, v0, v13
	s_waitcnt lgkmcnt(0)
	v_max_f32_e32 v13, v14, v14
	v_max_f32_e32 v12, v12, v13
	v_lshlrev_b32_e32 v13, 2, v18
	v_xor_b32_e32 v13, 8, v13
	v_lshlrev_b32_e32 v14, 2, v19
	ds_bpermute_b32 v13, v13, v0
	v_xor_b32_e32 v14, 8, v14
	ds_bpermute_b32 v14, v14, v12
	global_load_dwordx4 v[90:93], v154, s[52:53] offset:16
	global_load_dwordx4 v[94:97], v154, s[52:53]
	global_load_dwordx4 v[82:85], v154, s[52:53] offset:80
	global_load_dwordx4 v[86:89], v154, s[52:53] offset:64
	global_load_dwordx4 v[74:77], v154, s[52:53] offset:144
	global_load_dwordx4 v[78:81], v154, s[52:53] offset:128
	global_load_dwordx4 v[66:69], v154, s[52:53] offset:208
	global_load_dwordx4 v[70:73], v154, s[52:53] offset:192
	global_load_dwordx4 v[58:61], v154, s[52:53] offset:272
	global_load_dwordx4 v[62:65], v154, s[52:53] offset:256
	global_load_dwordx4 v[50:53], v154, s[52:53] offset:336
	global_load_dwordx4 v[54:57], v154, s[52:53] offset:320
	global_load_dwordx4 v[42:45], v154, s[52:53] offset:400
	global_load_dwordx4 v[46:49], v154, s[52:53] offset:384
	global_load_dwordx4 v[34:37], v154, s[52:53] offset:464
	global_load_dwordx4 v[38:41], v154, s[52:53] offset:448
	s_mov_b32 s7, 0x800000
	s_waitcnt lgkmcnt(1)
; DI u32 pack2(float a, float b) { f2_t v = {a, b}; bf2_t r = __builtin_convertvector(v, bf2_t); return __builtin_bit_cast(u32, r); }
; DI void mla_attn_item(const WsPtrs& W, const float* pgq, const float* pgk, int item, unsigned char* smem) {
;     ...
;   for (int of = 32; of > 0; of >>= 1) { gq = fmaxf(gq, shx(gq, of)); gk = fmaxf(gk, shx(gk, of)); }
;   const float M = 19.99f * gq * gk * 1.02f + 1.f;
;   bf16x8 qn[12];
;   {
;     const u16* Qr = W.QC + (tokb + q0 + r) * 1536 + hh * 192 + 8 * h;
;     u32x4 raw[12];
; #pragma unroll
;     for (int ks = 0; ks < 12; ++ks) raw[ks] = *(const u32x4*)(Qr + 16 * ks);
;     float ss = 0.f;
; #pragma unroll
;     for (int ks = 0; ks < 12; ++ks) {
;       float a;
;       a = bflo(raw[ks].x); ss += a * a; a = bfhi(raw[ks].x); ss += a * a; a = bflo(raw[ks].y); ss += a * a; a = bfhi(raw[ks].y); ss += a * a;
;       a = bflo(raw[ks].z); ss += a * a; a = bfhi(raw[ks].z); ss += a * a; a = bflo(raw[ks].w); ss += a * a; a = bfhi(raw[ks].w); ss += a * a;
;     }
;     ss += shx(ss, 32);
;     const float sc = rsqrtf(ss * (1.f / 192.f) + EPSV) * (0.07216878364870322f * LOG2E);
;     const float pos = (float)(q0 + r);
;     auto scaled = [&](int ks, float (&v)[8]) __attribute__((always_inline)) {
;       const f32x4 g0 = *(const f32x4*)(pgq + 16 * ks + 8 * h), g1 = *(const f32x4*)(pgq + 16 * ks + 8 * h + 4);
;       v[0] = bflo(raw[ks].x) * sc * g0.x; v[1] = bfhi(raw[ks].x) * sc * g0.y; v[2] = bflo(raw[ks].y) * sc * g0.z; v[3] = bfhi(raw[ks].y) * sc * g0.w;
;       v[4] = bflo(raw[ks].z) * sc * g1.x; v[5] = bfhi(raw[ks].z) * sc * g1.y; v[6] = bflo(raw[ks].w) * sc * g1.z; v[7] = bfhi(raw[ks].w) * sc * g1.w;
;     };
;     auto packed = [&](const float (&v)[8]) __attribute__((always_inline)) {
;       u32x4 p; p.x = pack2(v[0], v[1]); p.y = pack2(v[2], v[3]); p.z = pack2(v[4], v[5]); p.w = pack2(v[6], v[7]);
;       return __builtin_bit_cast(bf16x8, p);
;     };
; #pragma unroll
;     for (int ks = 0; ks < 8; ++ks) { float v[8]; scaled(ks, v); qn[ks] = packed(v); }
; #pragma unroll
;     for (int ks = 8; ks < 10; ++ks) {
;       float x1[8], x2[8]; scaled(ks, x1); scaled(ks + 2, x2);
; #pragma unroll
;       for (int i = 0; i < 8; ++i) {
;         float c, sn; rot_cs(pos, W.rope[8 + 16 * (ks - 8) + 8 * h + i], c, sn);
;         const float a = x1[i] * c - x2[i] * sn, b = x2[i] * c + x1[i] * sn;
;         x1[i] = a; x2[i] = b;
	v_max_f32_e32 v13, v13, v13
	v_max_f32_e32 v0, v0, v13
	s_waitcnt lgkmcnt(0)
	v_max_f32_e32 v13, v14, v14
	v_max_f32_e32 v12, v12, v13
	v_lshlrev_b32_e32 v13, 2, v20
	v_xor_b32_e32 v13, 4, v13
	v_lshlrev_b32_e32 v14, 2, v21
	ds_bpermute_b32 v13, v13, v0
	v_xor_b32_e32 v14, 4, v14
	ds_bpermute_b32 v14, v14, v12
	global_load_dwordx4 v[30:33], v154, s[52:53] offset:512
	global_load_dwordx4 v[26:29], v154, s[52:53] offset:528
	global_load_dwordx4 v[22:25], v154, s[52:53] offset:640
	global_load_dwordx4 v[18:21], v154, s[52:53] offset:656
	s_bfe_i32 s8, s15, 0x1c0000
	s_waitcnt lgkmcnt(1)
	v_max_f32_e32 v13, v13, v13
	v_max_f32_e32 v0, v0, v13
	s_waitcnt lgkmcnt(0)
	v_max_f32_e32 v13, v14, v14
	v_max_f32_e32 v12, v12, v13
	v_mul_f32_e32 v0, 0x419feb85, v0
	v_mul_f32_e32 v0, v0, v12
	s_mul_i32 s16, s6, 0xc00000
	s_mul_hi_i32 s15, s6, 0xc00000
	s_add_u32 s6, s11, s16
	s_mov_b32 s22, s20
	v_writelane_b32 v255, s22, 23
	s_mul_hi_i32 s19, s4, 0x8604000
	s_mul_i32 s17, s4, 0x9a04000
	v_writelane_b32 v255, s23, 24
	s_waitcnt vmcnt(35)
	v_and_b32_e32 v225, 0xffff0000, v98
	s_waitcnt vmcnt(33)
	v_lshlrev_b32_e32 v216, 16, v110
	v_and_b32_e32 v217, 0xffff0000, v110
	s_waitcnt vmcnt(31)
	v_lshlrev_b32_e32 v208, 16, v119
	s_waitcnt vmcnt(30)
	v_lshlrev_b32_e32 v204, 16, v123
	v_and_b32_e32 v205, 0xffff0000, v123
	s_waitcnt vmcnt(28)
	v_lshlrev_b32_e32 v196, 16, v131
	v_and_b32_e32 v197, 0xffff0000, v131
	s_waitcnt vmcnt(26)
	v_lshlrev_b32_e32 v176, 16, v147
	v_and_b32_e32 v177, 0xffff0000, v147
	s_waitcnt vmcnt(24)
	v_lshlrev_b32_e32 v174, 16, v143
	v_and_b32_e32 v175, 0xffff0000, v143
	s_waitcnt vmcnt(23)
	v_mul_f32_e32 v10, v2, v224
	v_floor_f32_e32 v10, v10
	v_fma_f32 v2, v2, v224, -v10
	v_cos_f32_e32 v150, v2
	v_sin_f32_e32 v156, v2
	v_mul_f32_e32 v2, v3, v224
	v_floor_f32_e32 v2, v2
	v_fma_f32 v2, v3, v224, -v2
	v_cos_f32_e32 v151, v2
	v_sin_f32_e32 v157, v2
	v_mul_f32_e32 v2, v4, v224
	v_floor_f32_e32 v2, v2
	v_fma_f32 v2, v4, v224, -v2
	v_cos_f32_e32 v152, v2
	v_sin_f32_e32 v160, v2
	v_mul_f32_e32 v2, v5, v224
	v_floor_f32_e32 v2, v2
	v_fma_f32 v2, v5, v224, -v2
	v_cos_f32_e32 v153, v2
	v_sin_f32_e32 v161, v2
	s_waitcnt vmcnt(22)
	v_mul_f32_e32 v2, v6, v224
	v_floor_f32_e32 v2, v2
	v_fma_f32 v2, v6, v224, -v2
	v_cos_f32_e32 v158, v2
	v_sin_f32_e32 v164, v2
	v_mul_f32_e32 v2, v7, v224
	v_floor_f32_e32 v2, v2
	v_fma_f32 v2, v7, v224, -v2
	v_cos_f32_e32 v159, v2
	v_sin_f32_e32 v165, v2
	v_mul_f32_e32 v2, v8, v224
	v_floor_f32_e32 v2, v2
	v_fma_f32 v2, v8, v224, -v2
	v_cos_f32_e32 v162, v2
	v_sin_f32_e32 v166, v2
	v_mul_f32_e32 v2, v9, v224
	v_floor_f32_e32 v2, v2
	v_fma_f32 v2, v9, v224, -v2
	v_cos_f32_e32 v163, v2
	v_sin_f32_e32 v167, v2
	global_load_dwordx4 v[14:17], v154, s[52:53] offset:576
	global_load_dwordx4 v[10:13], v154, s[52:53] offset:592
	global_load_dwordx4 v[6:9], v154, s[52:53] offset:704
	global_load_dwordx4 v[2:5], v154, s[52:53] offset:720
	s_waitcnt vmcnt(25)
	v_mul_f32_e32 v154, v168, v224
	v_floor_f32_e32 v154, v154
	v_fma_f32 v220, v168, v224, -v154
	v_mul_f32_e32 v168, v169, v224
	v_floor_f32_e32 v168, v168
	v_fma_f32 v239, v169, v224, -v168
	v_mul_f32_e32 v168, v170, v224
	v_floor_f32_e32 v168, v168
	v_fma_f32 v218, v170, v224, -v168
	v_mul_f32_e32 v168, v171, v224
	v_floor_f32_e32 v168, v168
	v_fma_f32 v238, v171, v224, -v168
	s_waitcnt vmcnt(24)
	v_mul_f32_e32 v168, v102, v224
	v_floor_f32_e32 v168, v168
	v_fma_f32 v219, v102, v224, -v168
	v_mul_f32_e32 v102, v103, v224
	v_floor_f32_e32 v102, v102
	v_fma_f32 v221, v103, v224, -v102
	v_lshlrev_b32_e32 v102, 16, v145
	v_and_b32_e32 v103, 0xffff0000, v145
	v_lshlrev_b32_e32 v170, 16, v144
	v_and_b32_e32 v171, 0xffff0000, v144
	v_lshlrev_b32_e32 v180, 16, v146
	v_and_b32_e32 v181, 0xffff0000, v146
	v_lshlrev_b32_e32 v178, 16, v142
	v_and_b32_e32 v179, 0xffff0000, v142
	v_lshlrev_b32_e32 v146, 16, v137
	v_and_b32_e32 v147, 0xffff0000, v137
	v_lshlrev_b32_e32 v184, 16, v136
	v_and_b32_e32 v185, 0xffff0000, v136
	v_lshlrev_b32_e32 v188, 16, v135
	v_and_b32_e32 v189, 0xffff0000, v135
	v_lshlrev_b32_e32 v192, 16, v134
	v_and_b32_e32 v193, 0xffff0000, v134
	v_lshlrev_b32_e32 v142, 16, v133
	v_and_b32_e32 v143, 0xffff0000, v133
	v_lshlrev_b32_e32 v144, 16, v132
	v_and_b32_e32 v145, 0xffff0000, v132
	v_lshlrev_b32_e32 v198, 16, v130
	v_and_b32_e32 v199, 0xffff0000, v130
	v_lshlrev_b32_e32 v134, 16, v125
	v_and_b32_e32 v135, 0xffff0000, v125
	v_lshlrev_b32_e32 v136, 16, v124
	v_and_b32_e32 v137, 0xffff0000, v124
	v_lshlrev_b32_e32 v206, 16, v122
	v_and_b32_e32 v207, 0xffff0000, v122
	v_lshlrev_b32_e32 v130, 16, v121
	v_and_b32_e32 v131, 0xffff0000, v121
	v_lshlrev_b32_e32 v132, 16, v120
	v_and_b32_e32 v133, 0xffff0000, v120
	v_and_b32_e32 v209, 0xffff0000, v119
	v_lshlrev_b32_e32 v210, 16, v118
	v_and_b32_e32 v211, 0xffff0000, v118
	v_lshlrev_b32_e32 v122, 16, v113
	v_and_b32_e32 v123, 0xffff0000, v113
	v_lshlrev_b32_e32 v124, 16, v112
	v_and_b32_e32 v125, 0xffff0000, v112
	v_lshlrev_b32_e32 v112, 16, v111
	v_and_b32_e32 v113, 0xffff0000, v111
	v_lshlrev_b32_e32 v110, 16, v109
	v_and_b32_e32 v111, 0xffff0000, v109
	v_lshlrev_b32_e32 v118, 16, v108
	v_and_b32_e32 v119, 0xffff0000, v108
	v_lshlrev_b32_e32 v108, 16, v107
	v_and_b32_e32 v109, 0xffff0000, v107
	v_lshlrev_b32_e32 v120, 16, v106
	v_and_b32_e32 v121, 0xffff0000, v106
	v_lshlrev_b32_e32 v106, 16, v101
	v_and_b32_e32 v107, 0xffff0000, v101
	v_mul_f32_e32 v101, v104, v224
	v_floor_f32_e32 v101, v101
	v_fma_f32 v227, v104, v224, -v101
	v_mul_f32_e32 v101, v105, v224
	v_floor_f32_e32 v101, v101
	v_fma_f32 v230, v105, v224, -v101
	v_lshlrev_b32_e32 v224, 16, v98
	v_lshlrev_b32_e32 v168, 16, v149
	v_and_b32_e32 v169, 0xffff0000, v149
; DI float bflo(u32 v) { return __uint_as_float(v << 16); }
; DI float bfhi(u32 v) { return __uint_as_float(v & 0xffff0000u); }
; DI float shx(float v, int k) { return __int_as_float(__builtin_amdgcn_ds_bpermute((lane_id_l() ^ k) << 2, __float_as_int(v))); }
; DI void mla_attn_item(const WsPtrs& W, const float* pgq, const float* pgk, int item, unsigned char* smem) {
;     ...
;     float ss = 0.f;
; #pragma unroll
;     for (int ks = 0; ks < 12; ++ks) {
;       float a;
;       a = bflo(raw[ks].x); ss += a * a; a = bfhi(raw[ks].x); ss += a * a; a = bflo(raw[ks].y); ss += a * a; a = bfhi(raw[ks].y); ss += a * a;
;       a = bflo(raw[ks].z); ss += a * a; a = bfhi(raw[ks].z); ss += a * a; a = bflo(raw[ks].w); ss += a * a; a = bfhi(raw[ks].w); ss += a * a;
;     }
;     ss += shx(ss, 32);
;     const float sc = rsqrtf(ss * (1.f / 192.f) + EPSV) * (0.07216878364870322f * LOG2E);
	v_lshlrev_b32_e32 v172, 16, v148
	v_and_b32_e32 v173, 0xffff0000, v148
	v_lshlrev_b32_e32 v148, 16, v141
	v_and_b32_e32 v149, 0xffff0000, v141
	v_lshlrev_b32_e32 v186, 16, v140
	v_and_b32_e32 v187, 0xffff0000, v140
	v_lshlrev_b32_e32 v190, 16, v139
	v_and_b32_e32 v191, 0xffff0000, v139
	v_lshlrev_b32_e32 v194, 16, v138
	v_and_b32_e32 v195, 0xffff0000, v138
	v_lshlrev_b32_e32 v138, 16, v129
	v_and_b32_e32 v139, 0xffff0000, v129
	v_lshlrev_b32_e32 v140, 16, v128
	v_and_b32_e32 v141, 0xffff0000, v128
	v_lshlrev_b32_e32 v200, 16, v127
	v_and_b32_e32 v201, 0xffff0000, v127
	v_lshlrev_b32_e32 v202, 16, v126
	v_and_b32_e32 v203, 0xffff0000, v126
	v_lshlrev_b32_e32 v126, 16, v117
	v_and_b32_e32 v127, 0xffff0000, v117
	v_lshlrev_b32_e32 v128, 16, v116
	v_and_b32_e32 v129, 0xffff0000, v116
	v_lshlrev_b32_e32 v116, 16, v99
	v_and_b32_e32 v117, 0xffff0000, v99
	v_pk_mul_f32 v[98:99], v[224:225], v[224:225]
	v_lshlrev_b32_e32 v212, 16, v115
	v_and_b32_e32 v213, 0xffff0000, v115
	v_lshlrev_b32_e32 v214, 16, v114
	v_and_b32_e32 v215, 0xffff0000, v114
	v_lshlrev_b32_e32 v114, 16, v100
	v_and_b32_e32 v115, 0xffff0000, v100
	v_add_f32_e32 v100, v99, v98
	v_pk_mul_f32 v[98:99], v[116:117], v[116:117]
	v_cos_f32_e32 v154, v220
	v_add_f32_e32 v98, v98, v100
	v_add_f32_e32 v100, v99, v98
	v_pk_mul_f32 v[98:99], v[114:115], v[114:115]
	v_sin_f32_e32 v101, v239
	v_add_f32_e32 v98, v98, v100
	v_add_f32_e32 v100, v99, v98
	v_pk_mul_f32 v[98:99], v[106:107], v[106:107]
	v_sin_f32_e32 v105, v238
	v_add_f32_e32 v98, v98, v100
	v_add_f32_e32 v100, v99, v98
	v_pk_mul_f32 v[98:99], v[120:121], v[120:121]
	s_nop 0
	v_add_f32_e32 v98, v98, v100
	v_add_f32_e32 v100, v99, v98
	v_pk_mul_f32 v[98:99], v[108:109], v[108:109]
	s_nop 0
	v_add_f32_e32 v98, v98, v100
	v_add_f32_e32 v100, v99, v98
	v_pk_mul_f32 v[98:99], v[118:119], v[118:119]
	s_nop 0
	v_add_f32_e32 v98, v98, v100
	v_add_f32_e32 v100, v99, v98
	v_pk_mul_f32 v[98:99], v[110:111], v[110:111]
	s_nop 0
	v_add_f32_e32 v98, v98, v100
	v_add_f32_e32 v100, v99, v98
	v_pk_mul_f32 v[98:99], v[216:217], v[216:217]
	s_nop 0
	v_add_f32_e32 v98, v98, v100
	v_add_f32_e32 v100, v99, v98
	v_pk_mul_f32 v[98:99], v[112:113], v[112:113]
	s_nop 0
	v_add_f32_e32 v98, v98, v100
	v_add_f32_e32 v100, v99, v98
	v_pk_mul_f32 v[98:99], v[124:125], v[124:125]
	s_nop 0
	v_add_f32_e32 v98, v98, v100
	v_add_f32_e32 v100, v99, v98
	v_pk_mul_f32 v[98:99], v[122:123], v[122:123]
	s_nop 0
	v_add_f32_e32 v98, v98, v100
	v_add_f32_e32 v100, v99, v98
	v_pk_mul_f32 v[98:99], v[214:215], v[214:215]
	s_nop 0
	v_add_f32_e32 v98, v98, v100
	v_add_f32_e32 v100, v99, v98
	v_pk_mul_f32 v[98:99], v[212:213], v[212:213]
	s_nop 0
	v_add_f32_e32 v98, v98, v100
	v_add_f32_e32 v100, v99, v98
	v_pk_mul_f32 v[98:99], v[128:129], v[128:129]
	s_nop 0
	v_add_f32_e32 v98, v98, v100
	v_add_f32_e32 v100, v99, v98
	v_pk_mul_f32 v[98:99], v[126:127], v[126:127]
	s_nop 0
	v_add_f32_e32 v98, v98, v100
	v_add_f32_e32 v100, v99, v98
	v_pk_mul_f32 v[98:99], v[210:211], v[210:211]
	s_nop 0
	v_add_f32_e32 v98, v98, v100
	v_add_f32_e32 v100, v99, v98
	v_pk_mul_f32 v[98:99], v[208:209], v[208:209]
	s_nop 0
	v_add_f32_e32 v98, v98, v100
	v_add_f32_e32 v100, v99, v98
	v_pk_mul_f32 v[98:99], v[132:133], v[132:133]
	s_nop 0
	v_add_f32_e32 v98, v98, v100
	v_add_f32_e32 v100, v99, v98
	v_pk_mul_f32 v[98:99], v[130:131], v[130:131]
	s_nop 0
	v_add_f32_e32 v98, v98, v100
	v_add_f32_e32 v100, v99, v98
	v_pk_mul_f32 v[98:99], v[206:207], v[206:207]
	s_nop 0
	v_add_f32_e32 v98, v98, v100
	v_add_f32_e32 v100, v99, v98
	v_pk_mul_f32 v[98:99], v[204:205], v[204:205]
	s_nop 0
	v_add_f32_e32 v98, v98, v100
	v_add_f32_e32 v100, v99, v98
	v_pk_mul_f32 v[98:99], v[136:137], v[136:137]
	s_nop 0
	v_add_f32_e32 v98, v98, v100
	v_add_f32_e32 v100, v99, v98
	v_pk_mul_f32 v[98:99], v[134:135], v[134:135]
	s_nop 0
	v_add_f32_e32 v98, v98, v100
	v_add_f32_e32 v100, v99, v98
	v_pk_mul_f32 v[98:99], v[202:203], v[202:203]
	s_nop 0
	v_add_f32_e32 v98, v98, v100
	v_add_f32_e32 v100, v99, v98
	v_pk_mul_f32 v[98:99], v[200:201], v[200:201]
	s_nop 0
	v_add_f32_e32 v98, v98, v100
	v_add_f32_e32 v100, v99, v98
	v_pk_mul_f32 v[98:99], v[140:141], v[140:141]
	s_nop 0
	v_add_f32_e32 v98, v98, v100
	v_add_f32_e32 v100, v99, v98
	v_pk_mul_f32 v[98:99], v[138:139], v[138:139]
	s_nop 0
	v_add_f32_e32 v98, v98, v100
	v_add_f32_e32 v100, v99, v98
	v_pk_mul_f32 v[98:99], v[198:199], v[198:199]
	s_nop 0
	v_add_f32_e32 v98, v98, v100
	v_add_f32_e32 v100, v99, v98
	v_pk_mul_f32 v[98:99], v[196:197], v[196:197]
	s_nop 0
	v_add_f32_e32 v98, v98, v100
	v_add_f32_e32 v100, v99, v98
	v_pk_mul_f32 v[98:99], v[144:145], v[144:145]
	s_nop 0
	v_add_f32_e32 v98, v98, v100
	v_add_f32_e32 v100, v99, v98
	v_pk_mul_f32 v[98:99], v[142:143], v[142:143]
	s_nop 0
	v_add_f32_e32 v98, v98, v100
	v_add_f32_e32 v100, v99, v98
	v_pk_mul_f32 v[98:99], v[194:195], v[194:195]
	s_nop 0
	v_add_f32_e32 v98, v98, v100
	v_add_f32_e32 v100, v99, v98
	v_pk_mul_f32 v[98:99], v[190:191], v[190:191]
	s_nop 0
	v_add_f32_e32 v98, v98, v100
	v_add_f32_e32 v100, v99, v98
	v_pk_mul_f32 v[98:99], v[186:187], v[186:187]
	s_nop 0
	v_add_f32_e32 v98, v98, v100
	v_add_f32_e32 v100, v99, v98
	v_pk_mul_f32 v[98:99], v[148:149], v[148:149]
	s_nop 0
	v_add_f32_e32 v98, v98, v100
	v_add_f32_e32 v100, v99, v98
	v_pk_mul_f32 v[98:99], v[180:181], v[180:181]
	s_nop 0
	v_add_f32_e32 v98, v98, v100
	v_add_f32_e32 v100, v99, v98
	v_pk_mul_f32 v[98:99], v[176:177], v[176:177]
	s_nop 0
	v_add_f32_e32 v98, v98, v100
	v_add_f32_e32 v100, v99, v98
	v_pk_mul_f32 v[98:99], v[172:173], v[172:173]
	s_nop 0
	v_add_f32_e32 v98, v98, v100
	v_add_f32_e32 v100, v99, v98
	v_pk_mul_f32 v[98:99], v[168:169], v[168:169]
	s_nop 0
	v_add_f32_e32 v98, v98, v100
	v_add_f32_e32 v100, v99, v98
	v_pk_mul_f32 v[98:99], v[192:193], v[192:193]
	s_nop 0
	v_add_f32_e32 v98, v98, v100
	v_add_f32_e32 v100, v99, v98
	v_pk_mul_f32 v[98:99], v[188:189], v[188:189]
	s_nop 0
	v_add_f32_e32 v98, v98, v100
	v_add_f32_e32 v100, v99, v98
	v_pk_mul_f32 v[98:99], v[184:185], v[184:185]
	s_nop 0
	v_add_f32_e32 v98, v98, v100
	v_add_f32_e32 v100, v99, v98
	v_pk_mul_f32 v[98:99], v[146:147], v[146:147]
	s_nop 0
	v_add_f32_e32 v98, v98, v100
	v_add_f32_e32 v100, v99, v98
	v_pk_mul_f32 v[98:99], v[178:179], v[178:179]
	s_nop 0
	v_add_f32_e32 v98, v98, v100
	v_add_f32_e32 v100, v99, v98
	v_pk_mul_f32 v[98:99], v[174:175], v[174:175]
	s_nop 0
	v_add_f32_e32 v98, v98, v100
	v_add_f32_e32 v100, v99, v98
	v_pk_mul_f32 v[98:99], v[170:171], v[170:171]
	s_nop 0
	v_add_f32_e32 v98, v98, v100
	v_add_f32_e32 v100, v99, v98
	v_pk_mul_f32 v[98:99], v[102:103], v[102:103]
	s_nop 0
	v_add_f32_e32 v98, v98, v100
	v_add_f32_e32 v99, v99, v98
	ds_bpermute_b32 v104, v155, v99
	v_sin_f32_e32 v100, v220
	v_cos_f32_e32 v98, v218
	v_cos_f32_e32 v155, v239
	s_waitcnt lgkmcnt(0)
; DI u32 pack2(float a, float b) { f2_t v = {a, b}; bf2_t r = __builtin_convertvector(v, bf2_t); return __builtin_bit_cast(u32, r); }
; DI float bflo(u32 v) { return __uint_as_float(v << 16); }
; DI float bfhi(u32 v) { return __uint_as_float(v & 0xffff0000u); }
; DI void mla_attn_item(const WsPtrs& W, const float* pgq, const float* pgk, int item, unsigned char* smem) {
;     ...
;     const float sc = rsqrtf(ss * (1.f / 192.f) + EPSV) * (0.07216878364870322f * LOG2E);
;     const float pos = (float)(q0 + r);
;     auto scaled = [&](int ks, float (&v)[8]) __attribute__((always_inline)) {
;       const f32x4 g0 = *(const f32x4*)(pgq + 16 * ks + 8 * h), g1 = *(const f32x4*)(pgq + 16 * ks + 8 * h + 4);
;       v[0] = bflo(raw[ks].x) * sc * g0.x; v[1] = bfhi(raw[ks].x) * sc * g0.y; v[2] = bflo(raw[ks].y) * sc * g0.z; v[3] = bfhi(raw[ks].y) * sc * g0.w;
;       v[4] = bflo(raw[ks].z) * sc * g1.x; v[5] = bfhi(raw[ks].z) * sc * g1.y; v[6] = bflo(raw[ks].w) * sc * g1.z; v[7] = bfhi(raw[ks].w) * sc * g1.w;
;     };
;     auto packed = [&](const float (&v)[8]) __attribute__((always_inline)) {
;       u32x4 p; p.x = pack2(v[0], v[1]); p.y = pack2(v[2], v[3]); p.z = pack2(v[4], v[5]); p.w = pack2(v[6], v[7]);
;       return __builtin_bit_cast(bf16x8, p);
;     };
; #pragma unroll
;     for (int ks = 0; ks < 8; ++ks) { float v[8]; scaled(ks, v); qn[ks] = packed(v); }
; #pragma unroll
;     for (int ks = 8; ks < 10; ++ks) {
;       float x1[8], x2[8]; scaled(ks, x1); scaled(ks + 2, x2);
; #pragma unroll
;       for (int i = 0; i < 8; ++i) {
;         float c, sn; rot_cs(pos, W.rope[8 + 16 * (ks - 8) + 8 * h + i], c, sn);
;         const float a = x1[i] * c - x2[i] * sn, b = x2[i] * c + x1[i] * sn;
;         x1[i] = a; x2[i] = b;
;       }
;       qn[ks] = packed(x1); qn[ks + 2] = packed(x2);
;     }
;   }
;   if (M <= 56.f)
	v_add_f32_e32 v99, v99, v104
	v_fmamk_f32 v99, v99, 0x3baaaaab, v228
	v_mul_f32_e32 v104, 0x4b800000, v99
	v_cmp_gt_f32_e32 vcc, s7, v99
	s_mov_b32 s7, 0x3f828f5c
	s_nop 0
	v_cndmask_b32_e32 v99, v99, v104, vcc
	v_rsq_f32_e32 v220, v99
	v_sin_f32_e32 v104, v218
	v_cos_f32_e32 v99, v238
	v_mul_f32_e32 v218, 0x45800000, v220
	v_cndmask_b32_e32 v218, v220, v218, vcc
	v_mul_f32_e32 v226, 0x3dd53b94, v218
	v_pk_mul_f32 v[224:225], v[226:227], v[224:225] op_sel_hi:[0,1]
	s_waitcnt vmcnt(22)
	v_pk_mul_f32 v[224:225], v[94:95], v[224:225]
	v_pk_mul_f32 v[94:95], v[226:227], v[116:117] op_sel_hi:[0,1]
	v_pk_mul_f32 v[114:115], v[226:227], v[114:115] op_sel_hi:[0,1]
	v_pk_mul_f32 v[116:117], v[96:97], v[94:95]
	v_pk_mul_f32 v[90:91], v[90:91], v[114:115]
	v_cvt_pk_bf16_f32 v115, v116, v117
	v_cvt_pk_bf16_f32 v116, v90, v91
	v_pk_mul_f32 v[90:91], v[226:227], v[120:121] op_sel_hi:[0,1]
	s_waitcnt vmcnt(20)
	v_pk_mul_f32 v[86:87], v[86:87], v[90:91]
	v_pk_mul_f32 v[90:91], v[226:227], v[108:109] op_sel_hi:[0,1]
	v_pk_mul_f32 v[88:89], v[88:89], v[90:91]
	v_pk_mul_f32 v[90:91], v[226:227], v[118:119] op_sel_hi:[0,1]
	v_pk_mul_f32 v[82:83], v[82:83], v[90:91]
	v_cos_f32_e32 v218, v219
	v_cvt_pk_bf16_f32 v120, v82, v83
	v_pk_mul_f32 v[82:83], v[226:227], v[216:217] op_sel_hi:[0,1]
	s_waitcnt vmcnt(18)
	v_pk_mul_f32 v[78:79], v[78:79], v[82:83]
	v_pk_mul_f32 v[82:83], v[226:227], v[112:113] op_sel_hi:[0,1]
	v_pk_mul_f32 v[80:81], v[80:81], v[82:83]
	v_pk_mul_f32 v[82:83], v[226:227], v[124:125] op_sel_hi:[0,1]
	v_pk_mul_f32 v[74:75], v[74:75], v[82:83]
	v_sin_f32_e32 v220, v219
	v_cvt_pk_bf16_f32 v124, v74, v75
	v_pk_mul_f32 v[74:75], v[226:227], v[214:215] op_sel_hi:[0,1]
	s_waitcnt vmcnt(16)
	v_pk_mul_f32 v[70:71], v[70:71], v[74:75]
	v_pk_mul_f32 v[74:75], v[226:227], v[212:213] op_sel_hi:[0,1]
	v_pk_mul_f32 v[72:73], v[72:73], v[74:75]
	v_pk_mul_f32 v[74:75], v[226:227], v[128:129] op_sel_hi:[0,1]
	v_pk_mul_f32 v[66:67], v[66:67], v[74:75]
	v_cos_f32_e32 v219, v221
	v_cvt_pk_bf16_f32 v128, v66, v67
	v_pk_mul_f32 v[66:67], v[226:227], v[210:211] op_sel_hi:[0,1]
	s_waitcnt vmcnt(14)
	v_pk_mul_f32 v[62:63], v[62:63], v[66:67]
	v_pk_mul_f32 v[66:67], v[226:227], v[208:209] op_sel_hi:[0,1]
	v_pk_mul_f32 v[64:65], v[64:65], v[66:67]
	v_pk_mul_f32 v[66:67], v[226:227], v[132:133] op_sel_hi:[0,1]
	v_pk_mul_f32 v[58:59], v[58:59], v[66:67]
	v_sin_f32_e32 v221, v221
	v_cvt_pk_bf16_f32 v132, v58, v59
	v_pk_mul_f32 v[58:59], v[226:227], v[206:207] op_sel_hi:[0,1]
	s_waitcnt vmcnt(12)
	v_pk_mul_f32 v[54:55], v[54:55], v[58:59]
	v_pk_mul_f32 v[58:59], v[226:227], v[204:205] op_sel_hi:[0,1]
	v_pk_mul_f32 v[56:57], v[56:57], v[58:59]
	v_pk_mul_f32 v[58:59], v[226:227], v[136:137] op_sel_hi:[0,1]
	v_pk_mul_f32 v[50:51], v[50:51], v[58:59]
	v_sin_f32_e32 v96, v227
	v_cvt_pk_bf16_f32 v136, v50, v51
	v_pk_mul_f32 v[50:51], v[226:227], v[202:203] op_sel_hi:[0,1]
	s_waitcnt vmcnt(10)
	v_pk_mul_f32 v[46:47], v[46:47], v[50:51]
	v_pk_mul_f32 v[50:51], v[226:227], v[200:201] op_sel_hi:[0,1]
	v_pk_mul_f32 v[48:49], v[48:49], v[50:51]
	v_pk_mul_f32 v[50:51], v[226:227], v[140:141] op_sel_hi:[0,1]
	v_pk_mul_f32 v[42:43], v[42:43], v[50:51]
	v_sin_f32_e32 v97, v230
	v_cvt_pk_bf16_f32 v140, v42, v43
	v_pk_mul_f32 v[42:43], v[226:227], v[198:199] op_sel_hi:[0,1]
	s_waitcnt vmcnt(8)
	v_pk_mul_f32 v[38:39], v[38:39], v[42:43]
	v_pk_mul_f32 v[42:43], v[226:227], v[196:197] op_sel_hi:[0,1]
	v_pk_mul_f32 v[40:41], v[40:41], v[42:43]
	v_pk_mul_f32 v[42:43], v[226:227], v[144:145] op_sel_hi:[0,1]
	v_pk_mul_f32 v[34:35], v[34:35], v[42:43]
	v_pk_mul_f32 v[66:67], v[226:227], v[130:131] op_sel_hi:[0,1]
	v_cvt_pk_bf16_f32 v144, v34, v35
	v_pk_mul_f32 v[34:35], v[226:227], v[194:195] op_sel_hi:[0,1]
	s_waitcnt vmcnt(7)
	v_pk_mul_f32 v[30:31], v[30:31], v[34:35]
	v_pk_mul_f32 v[34:35], v[226:227], v[190:191] op_sel_hi:[0,1]
	v_pk_mul_f32 v[32:33], v[32:33], v[34:35]
	v_pk_mul_f32 v[34:35], v[226:227], v[186:187] op_sel_hi:[0,1]
	s_waitcnt vmcnt(6)
	v_pk_mul_f32 v[26:27], v[26:27], v[34:35]
	v_pk_mul_f32 v[34:35], v[226:227], v[148:149] op_sel_hi:[0,1]
	v_pk_mul_f32 v[28:29], v[28:29], v[34:35]
	v_pk_mul_f32 v[34:35], v[226:227], v[192:193] op_sel_hi:[0,1]
	s_waitcnt vmcnt(5)
	v_pk_mul_f32 v[22:23], v[22:23], v[34:35]
	v_pk_mul_f32 v[34:35], v[226:227], v[188:189] op_sel_hi:[0,1]
	v_pk_mul_f32 v[24:25], v[24:25], v[34:35]
	v_pk_mul_f32 v[34:35], v[226:227], v[184:185] op_sel_hi:[0,1]
	s_waitcnt vmcnt(4)
	v_pk_mul_f32 v[18:19], v[18:19], v[34:35]
	v_pk_mul_f32 v[34:35], v[226:227], v[146:147] op_sel_hi:[0,1]
	v_pk_mul_f32 v[20:21], v[20:21], v[34:35]
	v_pk_mul_f32 v[34:35], v[156:157], v[30:31]
	v_cos_f32_e32 v94, v227
	v_pk_fma_f32 v[34:35], v[150:151], v[22:23], v[34:35]
	v_pk_mul_f32 v[22:23], v[156:157], v[22:23]
	v_cos_f32_e32 v95, v230
	v_pk_fma_f32 v[22:23], v[150:151], v[30:31], v[22:23] neg_lo:[0,0,1] neg_hi:[0,0,1]
	v_pk_mul_f32 v[30:31], v[160:161], v[32:33]
	v_pk_mul_f32 v[60:61], v[60:61], v[66:67]
	v_pk_fma_f32 v[30:31], v[152:153], v[24:25], v[30:31]
	v_pk_mul_f32 v[24:25], v[160:161], v[24:25]
	v_fma_f32 v66, v0, s7, 1.0
	v_pk_fma_f32 v[24:25], v[152:153], v[32:33], v[24:25] neg_lo:[0,0,1] neg_hi:[0,0,1]
	v_pk_mul_f32 v[32:33], v[164:165], v[26:27]
	s_mov_b32 s7, 0x42600000
	v_pk_fma_f32 v[32:33], v[158:159], v[18:19], v[32:33]
	v_pk_mul_f32 v[18:19], v[164:165], v[18:19]
	v_cmp_ge_f32_e32 vcc, s7, v66
	v_pk_fma_f32 v[18:19], v[158:159], v[26:27], v[18:19] neg_lo:[0,0,1] neg_hi:[0,0,1]
	s_addc_u32 s7, s12, s15
	v_cvt_pk_bf16_f32 v148, v18, v19
	v_pk_mul_f32 v[18:19], v[226:227], v[180:181] op_sel_hi:[0,1]
	s_waitcnt vmcnt(3)
;     ...
;   for (int i = 0; i < NKL; ++i) { int c = tid + NTHR * i; int row = c / KCH, kc = c % KCH; koff[i] = (u32)(row * ldk + 8 * kc) * 2u; klds[i] = row * KST + 8 * kc; }
;   const u32 voff = (u32)((tid >> 3) * 4096 + 8 * (tid & 7)) * 2u;
;   const int vlds = 64 * KST + (tid >> 3) * 72 + 8 * (tid & 7);
;   auto gload = [&](int k0) __attribute__((always_inline)) {
;     const char* kb = (const char*)Kg + (size_t)k0 * ldk * 2;
; #pragma unroll
;     for (int i = 0; i < NKL; ++i) rk[i] = *(const u32x4*)(kb + koff[i]);
;     const char* vb = (const char*)VTg + (size_t)k0 * 2;
; #pragma unroll
;     for (int i = 0; i < 2; ++i) rv[i] = *(const u32x4*)(vb + (size_t)i * 64 * 4096 * 2 + voff);
;   };
;   auto lstore = [&](int b) __attribute__((always_inline)) {
;     u16* St = S0 + b * STG;
; #pragma unroll
;     for (int i = 0; i < NKL; ++i) *(u32x4*)(St + klds[i]) = rk[i];
; #pragma unroll
;     for (int i = 0; i < 2; ++i) *(u32x4*)(St + vlds + i * 64 * 72) = rv[i];
;   };
;   gload(kt0 * 64);
;   __syncthreads();
;   lstore(0);
;   gload((kt0 + 1) * 64);
; DI void mla_attn_item(const WsPtrs& W, const float* pgq, const float* pgk, int item, unsigned char* smem) {
;     ...
;       qn[ks] = packed(x1); qn[ks + 2] = packed(x2);
;     }
;   }
;   if (M <= 56.f)
;     attn_core<192, 192, 1>(W.QC + (tokb + q0) * 1536 + hh * 192, 1536, W.KC + tokb * 1536 + hh * 192, 1536,
;                            W.CVT + (size_t)bh * 128 * 4096, 0, q0, M, o, l, smem, 0, 64, true, qn);
	v_pk_mul_f32 v[14:15], v[14:15], v[18:19]
	v_pk_mul_f32 v[18:19], v[226:227], v[176:177] op_sel_hi:[0,1]
	v_pk_mul_f32 v[16:17], v[16:17], v[18:19]
	v_pk_mul_f32 v[18:19], v[226:227], v[172:173] op_sel_hi:[0,1]
	s_waitcnt vmcnt(2)
	v_pk_mul_f32 v[10:11], v[10:11], v[18:19]
	v_pk_mul_f32 v[18:19], v[226:227], v[168:169] op_sel_hi:[0,1]
	v_pk_mul_f32 v[12:13], v[12:13], v[18:19]
	v_pk_mul_f32 v[18:19], v[226:227], v[178:179] op_sel_hi:[0,1]
	s_waitcnt vmcnt(1)
	v_pk_mul_f32 v[6:7], v[6:7], v[18:19]
	v_pk_mul_f32 v[18:19], v[226:227], v[174:175] op_sel_hi:[0,1]
	v_pk_mul_f32 v[8:9], v[8:9], v[18:19]
	v_pk_mul_f32 v[18:19], v[226:227], v[170:171] op_sel_hi:[0,1]
	s_waitcnt vmcnt(0)
	v_pk_mul_f32 v[2:3], v[2:3], v[18:19]
	v_pk_mul_f32 v[18:19], v[226:227], v[102:103] op_sel_hi:[0,1]
	v_pk_mul_f32 v[4:5], v[4:5], v[18:19]
	v_pk_mul_f32 v[18:19], v[100:101], v[14:15]
	s_add_u32 s6, s6, s20
	v_pk_fma_f32 v[18:19], v[154:155], v[6:7], v[18:19]
	v_pk_mul_f32 v[6:7], v[100:101], v[6:7]
	v_pk_mul_f32 v[26:27], v[166:167], v[28:29]
	v_pk_fma_f32 v[6:7], v[154:155], v[14:15], v[6:7] neg_lo:[0,0,1] neg_hi:[0,0,1]
	v_pk_mul_f32 v[14:15], v[104:105], v[16:17]
	s_addc_u32 s7, s7, 0
	v_pk_fma_f32 v[14:15], v[98:99], v[8:9], v[14:15]
	v_pk_mul_f32 v[8:9], v[104:105], v[8:9]
	s_ashr_i32 s9, s8, 31
	v_pk_fma_f32 v[8:9], v[98:99], v[16:17], v[8:9] neg_lo:[0,0,1] neg_hi:[0,0,1]
	v_pk_mul_f32 v[16:17], v[220:221], v[10:11]
	v_pk_mul_f32 v[106:107], v[226:227], v[106:107] op_sel_hi:[0,1]
	v_pk_fma_f32 v[16:17], v[218:219], v[2:3], v[16:17]
	v_pk_mul_f32 v[2:3], v[220:221], v[2:3]
	v_pk_mul_f32 v[90:91], v[226:227], v[110:111] op_sel_hi:[0,1]
	v_pk_fma_f32 v[2:3], v[218:219], v[10:11], v[2:3] neg_lo:[0,0,1] neg_hi:[0,0,1]
	v_pk_mul_f32 v[10:11], v[96:97], v[12:13]
	v_pk_mul_f32 v[82:83], v[226:227], v[122:123] op_sel_hi:[0,1]
	v_pk_mul_f32 v[74:75], v[226:227], v[126:127] op_sel_hi:[0,1]
	v_pk_mul_f32 v[58:59], v[226:227], v[134:135] op_sel_hi:[0,1]
	v_pk_mul_f32 v[50:51], v[226:227], v[138:139] op_sel_hi:[0,1]
	v_pk_mul_f32 v[42:43], v[226:227], v[142:143] op_sel_hi:[0,1]
	v_pk_fma_f32 v[26:27], v[162:163], v[20:21], v[26:27]
	v_pk_mul_f32 v[20:21], v[166:167], v[20:21]
	v_pk_fma_f32 v[10:11], v[94:95], v[4:5], v[10:11]
	v_pk_mul_f32 v[4:5], v[96:97], v[4:5]
	s_lshl_b64 s[8:9], s[8:9], 20
	v_pk_mul_f32 v[92:93], v[92:93], v[106:107]
	v_pk_mul_f32 v[84:85], v[84:85], v[90:91]
	v_pk_mul_f32 v[76:77], v[76:77], v[82:83]
	v_pk_mul_f32 v[68:69], v[68:69], v[74:75]
	v_pk_mul_f32 v[52:53], v[52:53], v[58:59]
	v_pk_mul_f32 v[44:45], v[44:45], v[50:51]
	v_pk_mul_f32 v[36:37], v[36:37], v[42:43]
	v_pk_fma_f32 v[20:21], v[162:163], v[28:29], v[20:21] neg_lo:[0,0,1] neg_hi:[0,0,1]
	v_pk_fma_f32 v[4:5], v[94:95], v[12:13], v[4:5] neg_lo:[0,0,1] neg_hi:[0,0,1]
	s_add_u32 s8, s5, s8
	v_cvt_pk_bf16_f32 v114, v224, v225
	v_cvt_pk_bf16_f32 v117, v92, v93
	v_cvt_pk_bf16_f32 v118, v86, v87
	v_cvt_pk_bf16_f32 v119, v88, v89
	v_cvt_pk_bf16_f32 v121, v84, v85
	v_cvt_pk_bf16_f32 v122, v78, v79
	v_cvt_pk_bf16_f32 v123, v80, v81
	v_cvt_pk_bf16_f32 v125, v76, v77
	v_cvt_pk_bf16_f32 v126, v70, v71
	v_cvt_pk_bf16_f32 v127, v72, v73
	v_cvt_pk_bf16_f32 v129, v68, v69
	v_cvt_pk_bf16_f32 v130, v62, v63
	v_cvt_pk_bf16_f32 v131, v64, v65
	v_cvt_pk_bf16_f32 v133, v60, v61
	v_cvt_pk_bf16_f32 v134, v54, v55
	v_cvt_pk_bf16_f32 v135, v56, v57
	v_cvt_pk_bf16_f32 v137, v52, v53
	v_cvt_pk_bf16_f32 v138, v46, v47
	v_cvt_pk_bf16_f32 v139, v48, v49
	v_cvt_pk_bf16_f32 v141, v44, v45
	v_cvt_pk_bf16_f32 v142, v38, v39
	v_cvt_pk_bf16_f32 v143, v40, v41
	v_cvt_pk_bf16_f32 v145, v36, v37
	v_cvt_pk_bf16_f32 v146, v22, v23
	v_cvt_pk_bf16_f32 v147, v24, v25
	v_cvt_pk_bf16_f32 v149, v20, v21
	v_cvt_pk_bf16_f32 v150, v34, v35
	v_cvt_pk_bf16_f32 v151, v30, v31
	v_cvt_pk_bf16_f32 v152, v32, v33
	v_cvt_pk_bf16_f32 v153, v26, v27
	v_cvt_pk_bf16_f32 v154, v6, v7
	v_cvt_pk_bf16_f32 v155, v8, v9
	v_cvt_pk_bf16_f32 v156, v2, v3
	v_cvt_pk_bf16_f32 v157, v4, v5
	v_cvt_pk_bf16_f32 v158, v18, v19
	v_cvt_pk_bf16_f32 v159, v14, v15
	v_cvt_pk_bf16_f32 v160, v16, v17
	v_cvt_pk_bf16_f32 v161, v10, v11
	s_addc_u32 s9, s14, s9
	s_mul_i32 s20, s4, 0x8604000
	s_mul_hi_i32 s14, s4, 0x9a04000
	s_and_saveexec_b64 s[4:5], vcc
	s_xor_b64 s[4:5], exec, s[4:5]
	s_cbranch_execz .LBB0_597
	v_mov_b32_e32 v23, v250
	s_mov_b32 s22, 0x2aaaaaab
	s_movk_i32 s21, 0x600
	v_mul_hi_i32 v0, v23, s22
	v_lshrrev_b32_e32 v2, 31, v0
	v_ashrrev_i32_e32 v0, 2, v0
	v_add_u32_e32 v25, v0, v2
	v_mul_lo_u32 v0, v25, 24
	v_sub_u32_e32 v0, v23, v0
	v_mul_lo_u32 v2, v25, s21
	v_lshl_add_u32 v22, v0, 3, v2
	v_add_u32_e32 v2, 0x200, v23
	v_mul_hi_i32 v3, v2, s22
	v_lshrrev_b32_e32 v4, 31, v3
	v_ashrrev_i32_e32 v3, 2, v3
	v_add_u32_e32 v29, v3, v4
	v_mul_lo_u32 v3, v29, 24
	v_sub_u32_e32 v2, v2, v3
	v_mul_lo_u32 v3, v29, s21
	v_lshl_add_u32 v24, v2, 3, v3
	v_add_u32_e32 v2, 0x400, v23
	v_mul_hi_i32 v3, v2, s22
	v_lshrrev_b32_e32 v4, 31, v3
	v_ashrrev_i32_e32 v3, 2, v3
	v_add_u32_e32 v33, v3, v4
	v_mul_lo_u32 v3, v33, 24
	v_sub_u32_e32 v2, v2, v3
	v_mul_lo_u32 v3, v33, s21
	v_lshl_add_u32 v28, v2, 3, v3
	v_ashrrev_i32_e32 v38, 3, v23
	v_lshlrev_b32_e32 v2, 3, v23
	v_and_b32_e32 v32, 56, v2
	v_lshlrev_b32_e32 v2, 13, v38
	v_lshl_or_b32 v34, v32, 1, v2
	v_mov_b32_e32 v35, v1
	v_lshl_add_u64 v[18:19], s[8:9], 0, v[34:35]
	s_mov_b32 s21, 0x80000
	v_add_co_u32_e32 v36, vcc, s21, v18
	s_add_u32 s22, s6, 0x30000
	v_lshlrev_b32_e32 v0, 1, v22
	v_lshlrev_b32_e32 v26, 1, v24
	v_lshlrev_b32_e32 v30, 1, v28
	v_addc_co_u32_e32 v37, vcc, 0, v19, vcc
	s_addc_u32 s23, s7, 0
	global_load_dwordx4 v[2:5], v0, s[6:7]
	global_load_dwordx4 v[6:9], v26, s[6:7]
	global_load_dwordx4 v[10:13], v30, s[6:7]
	global_load_dwordx4 v[14:17], v34, s[8:9]
	global_load_dwordx4 v[18:21], v[36:37], off
	s_barrier
; #define MFMA32(a, b, c) __builtin_amdgcn_mfma_f32_32x32x16_bf16((a), (b), (c), 0, 0, 0)
;     ...
;   for (int i = 0; i < NKL; ++i) { int c = tid + NTHR * i; int row = c / KCH, kc = c % KCH; koff[i] = (u32)(row * ldk + 8 * kc) * 2u; klds[i] = row * KST + 8 * kc; }
;   const u32 voff = (u32)((tid >> 3) * 4096 + 8 * (tid & 7)) * 2u;
;   const int vlds = 64 * KST + (tid >> 3) * 72 + 8 * (tid & 7);
;   auto gload = [&](int k0) __attribute__((always_inline)) {
;     const char* kb = (const char*)Kg + (size_t)k0 * ldk * 2;
; #pragma unroll
;     for (int i = 0; i < NKL; ++i) rk[i] = *(const u32x4*)(kb + koff[i]);
;     const char* vb = (const char*)VTg + (size_t)k0 * 2;
; #pragma unroll
;     for (int i = 0; i < 2; ++i) rv[i] = *(const u32x4*)(vb + (size_t)i * 64 * 4096 * 2 + voff);
;   };
;   auto lstore = [&](int b) __attribute__((always_inline)) {
;     u16* St = S0 + b * STG;
; #pragma unroll
;     for (int i = 0; i < NKL; ++i) *(u32x4*)(St + klds[i]) = rk[i];
; #pragma unroll
;     for (int i = 0; i < 2; ++i) *(u32x4*)(St + vlds + i * 64 * 72) = rv[i];
;   };
;   gload(kt0 * 64);
;   __syncthreads();
;   lstore(0);
;   gload((kt0 + 1) * 64);
;   __syncthreads();
;   const float qpos = (float)(qpos0 + r);
; #pragma unroll 1
;   for (int kt = 0; kt < nkt; ++kt) {
;     const u16* Ks = S0 + (kt & 1) * STG;
;     const u16* Vs = Ks + 64 * KST;
;     f32x16 st[2];
; #pragma unroll
;     for (int t2 = 0; t2 < 2; ++t2)
; #pragma unroll
;       for (int e = 0; e < 16; ++e) st[t2][e] = (MODE == 1) ? -dl : 0.f;
;     {
;       constexpr int BPT = NQ / 4;
;       constexpr int NBAT = 2 * BPT;
;       bf16x8 kf[2][4];
; #pragma unroll
;       for (int i = 0; i < 4; ++i) kf[0][i] = *(const bf16x8*)(Ks + r * KST + kcol_off + 16 * i + 8 * h);
; #pragma unroll
;       for (int g = 0; g < NBAT; ++g) {
;         if (g + 1 < NBAT) {
;           const int t2n = (g + 1) / BPT, bn = (g + 1) % BPT;
; #pragma unroll
;           for (int i = 0; i < 4; ++i) kf[(g + 1) & 1][i] = *(const bf16x8*)(Ks + (32 * t2n + r) * KST + kcol_off + 16 * (4 * bn + i) + 8 * h);
;         }
;         __builtin_amdgcn_sched_barrier(0);
;         const int t2 = g / BPT, b = g % BPT;
; #pragma unroll
;         for (int i = 0; i < 4; ++i) st[t2] = MFMA32(kf[g & 1][i], qf[4 * b + i], st[t2]);
;         __builtin_amdgcn_sched_barrier(0);
	global_load_dwordx4 v[162:165], v26, s[22:23]
	global_load_dwordx4 v[170:173], v30, s[22:23]
	global_load_dwordx4 v[174:177], v34, s[8:9] offset:128
	global_load_dwordx4 v[166:169], v0, s[22:23]
	global_load_dwordx4 v[178:181], v[36:37], off offset:128
	v_readlane_b32 s22, v255, 25
	s_or_b32 s22, s22, s13
	s_bfe_i32 s23, s22, 0x1001b
	s_bfe_i32 s22, s22, 0x1c0000
	s_lshl_b64 s[22:23], s[22:23], 20
	s_add_u32 s22, s20, s22
	s_addc_u32 s23, s19, s23
	v_and_b32_e32 v39, 31, v23
	v_lshrrev_b32_e32 v23, 2, v23
	v_mov_b32_e32 v192, v34
	v_add_u32_e32 v193, 0x80000, v34
	s_add_u32 s100, s22, s62
	s_addc_u32 s101, s23, s63
	s_add_u32 s100, s100, 0x7046000
	s_addc_u32 s101, s101, 0
	v_readlane_b32 s22, v255, 46
	v_and_b32_e32 v23, 8, v23
	s_movk_i32 s24, 0x48
	s_movk_i32 s26, 0xfac8
	s_add_u32 s22, s22, s17
	v_readlane_b32 s23, v255, 47
	v_mad_u64_u32 v[184:185], s[24:25], v38, s24, v[32:33]
	v_mad_u64_u32 v[186:187], s[24:25], v25, s26, v[22:23]
	s_addc_u32 s23, s23, s14
	v_mad_u64_u32 v[188:189], s[24:25], v29, s26, v[24:25]
	v_mad_u64_u32 v[190:191], s[24:25], v33, s26, v[28:29]
	v_lshl_add_u32 v22, v186, 1, 64
	s_add_u32 s22, s22, s16
	v_mov_b32_e32 v27, v1
	v_mov_b32_e32 v31, v1
	v_xor_b32_e32 v66, 0x80000000, v66
	v_mul_u32_u24_e32 v40, 0xc8, v39
	v_lshl_add_u32 v32, v184, 1, 64
	v_lshl_add_u32 v24, v188, 1, 64
	v_lshl_add_u32 v25, v190, 1, 64
	s_addc_u32 s23, s23, s15
	v_mov_b32_e32 v185, 0
	s_mov_b32 s21, 0
	v_mov_b32_e32 v67, v66
	v_mov_b32_e32 v68, v66
	v_mov_b32_e32 v69, v66
	v_mov_b32_e32 v70, v66
	v_mov_b32_e32 v71, v66
	v_mov_b32_e32 v72, v66
	v_mov_b32_e32 v73, v66
	v_mov_b32_e32 v74, v66
	v_mov_b32_e32 v75, v66
	s_waitcnt vmcnt(9)
	ds_write_b128 v22, v[2:5]
	s_waitcnt vmcnt(8)
	ds_write_b128 v24, v[6:9]
	s_waitcnt vmcnt(7)
	ds_write_b128 v25, v[10:13]
	s_waitcnt vmcnt(6)
	ds_write_b128 v32, v[14:17] offset:25600
	s_waitcnt vmcnt(5)
	ds_write_b128 v32, v[18:21] offset:34816
	v_lshlrev_b32_e32 v2, 8, v39
	v_mov_b32_e32 v76, v66
	v_mov_b32_e32 v77, v66
	v_mov_b32_e32 v78, v66
	v_mov_b32_e32 v79, v66
	v_mov_b32_e32 v80, v66
	v_mov_b32_e32 v81, v66
	v_mul_u32_u24_e32 v187, 0x190, v39
	v_sub_u32_e32 v189, 0, v2
	v_mov_b32_e32 v194, v0
	v_mov_b32_e32 v195, v26
	v_mov_b32_e32 v196, v30
	v_lshlrev_b32_e32 v0, 1, v40
	v_lshlrev_b32_e32 v191, 1, v23
	v_mov_b32_e32 v50, 0
	v_mov_b32_e32 v51, v185
	v_mov_b32_e32 v52, v185
	v_mov_b32_e32 v53, v185
	v_mov_b32_e32 v54, v185
	v_mov_b32_e32 v55, v185
	v_mov_b32_e32 v56, v185
	v_mov_b32_e32 v57, v185
	v_mov_b32_e32 v58, v185
	v_mov_b32_e32 v59, v185
	v_mov_b32_e32 v60, v185
	v_mov_b32_e32 v61, v185
	v_mov_b32_e32 v62, v185
	v_mov_b32_e32 v63, v185
	v_mov_b32_e32 v64, v185
	v_mov_b32_e32 v65, v185
	v_mov_b32_e32 v34, 0
	v_mov_b32_e32 v35, v185
	v_mov_b32_e32 v36, v185
	v_mov_b32_e32 v37, v185
	v_mov_b32_e32 v38, v185
	v_mov_b32_e32 v39, v185
	v_mov_b32_e32 v40, v185
	v_mov_b32_e32 v41, v185
	v_mov_b32_e32 v42, v185
	v_mov_b32_e32 v43, v185
	v_mov_b32_e32 v44, v185
	v_mov_b32_e32 v45, v185
	v_mov_b32_e32 v46, v185
	v_mov_b32_e32 v47, v185
	v_mov_b32_e32 v48, v185
	v_mov_b32_e32 v49, v185
	v_mov_b32_e32 v18, 0
	v_mov_b32_e32 v19, v185
	v_mov_b32_e32 v20, v185
	v_mov_b32_e32 v21, v185
	v_mov_b32_e32 v22, v185
	v_mov_b32_e32 v23, v185
	v_mov_b32_e32 v24, v185
	v_mov_b32_e32 v25, v185
	v_mov_b32_e32 v26, v185
	v_mov_b32_e32 v27, v185
	v_mov_b32_e32 v28, v185
	v_mov_b32_e32 v29, v185
	v_mov_b32_e32 v30, v185
	v_mov_b32_e32 v31, v185
	v_mov_b32_e32 v32, v185
	v_mov_b32_e32 v33, v185
	v_mov_b32_e32 v2, 0
	v_mov_b32_e32 v3, v185
	v_mov_b32_e32 v4, v185
	v_mov_b32_e32 v5, v185
	v_mov_b32_e32 v6, v185
	v_mov_b32_e32 v7, v185
	v_mov_b32_e32 v8, v185
	v_mov_b32_e32 v9, v185
	v_mov_b32_e32 v10, v185
	v_mov_b32_e32 v11, v185
	v_mov_b32_e32 v12, v185
	v_mov_b32_e32 v13, v185
	v_mov_b32_e32 v14, v185
	v_mov_b32_e32 v15, v185
	v_mov_b32_e32 v16, v185
	v_mov_b32_e32 v17, v185
	s_waitcnt lgkmcnt(0)
	s_barrier
	v_mov_b32_e32 v200, 0
	v_mov_b32_e32 v201, 0
	v_mov_b32_e32 v202, 0
	v_mov_b32_e32 v203, 0
	v_mov_b32_e32 v204, 0
	v_mov_b32_e32 v205, 0
	v_mov_b32_e32 v206, 0
	v_mov_b32_e32 v207, 0
	v_mov_b32_e32 v208, 0
	v_mov_b32_e32 v209, 0
	v_mov_b32_e32 v210, 0
	v_mov_b32_e32 v211, 0
	v_mov_b32_e32 v212, 0
	v_mov_b32_e32 v213, 0
	v_mov_b32_e32 v214, 0
	v_mov_b32_e32 v215, 0
	v_mov_b32_e32 v242, 0
	v_mov_b32_e32 v243, 0
	v_mov_b32_e32 v244, 0
	v_mov_b32_e32 v245, 0
	s_add_u32 vcc_lo, s22, s62
	s_addc_u32 vcc_hi, s23, s63
.LBB0_590:
	s_bitcmp1_b32 s21, 0
	s_cselect_b32 s22, 0xac00, 0
	s_add_i32 s22, s22, 64
	v_add3_u32 v220, s22, v0, v191
	ds_read_b128 v[98:101], v220
	ds_read_b128 v[102:105], v220 offset:32
	ds_read_b128 v[106:109], v220 offset:64
	ds_read_b128 v[110:113], v220 offset:96
	ds_read_b128 v[216:219], v220 offset:256
	ds_read_b128 v[224:227], v220 offset:288
	ds_read_b128 v[230:233], v220 offset:320
	ds_read_b128 v[238:241], v220 offset:352
	s_add_i32 s22, s21, 1
	s_bitcmp1_b32 s22, 0
	s_cselect_b32 s23, 0xac00, 0
	s_add_i32 s23, s23, 64
	v_mfma_f32_32x32x16_bf16 v[50:65], v[200:203], v[242:245], v[50:65]
	ds_read_b128 v[200:203], v220 offset:128
	v_lshl_add_u32 v246, v186, 1, s23
	v_lshl_add_u32 v247, v188, 1, s23
	v_mfma_f32_32x32x16_bf16 v[34:49], v[204:207], v[242:245], v[34:49]
	ds_read_b128 v[204:207], v220 offset:160
	v_lshl_add_u32 v248, v190, 1, s23
	v_lshl_add_u32 v249, v184, 1, s23
	s_waitcnt vmcnt(0)
	v_mfma_f32_32x32x16_bf16 v[18:33], v[208:211], v[242:245], v[18:33]
	ds_read_b128 v[208:211], v220 offset:192
	ds_write_b128 v246, v[166:169]
	ds_write_b128 v247, v[162:165]
	v_mfma_f32_32x32x16_bf16 v[2:17], v[212:215], v[242:245], v[2:17]
	ds_read_b128 v[212:215], v220 offset:224
	ds_write_b128 v248, v[170:173]
	ds_write_b128 v249, v[174:177] offset:25600
	s_waitcnt lgkmcnt(15)
	v_mfma_f32_32x32x16_bf16 v[82:97], v[98:101], v[114:117], v[66:81]
	ds_write_b128 v249, v[178:181] offset:34816
	s_waitcnt lgkmcnt(15)
	v_mfma_f32_32x32x16_bf16 v[82:97], v[102:105], v[118:121], v[82:97]
	s_waitcnt lgkmcnt(14)
	v_mfma_f32_32x32x16_bf16 v[82:97], v[106:109], v[122:125], v[82:97]
	s_waitcnt lgkmcnt(13)
	v_mfma_f32_32x32x16_bf16 v[82:97], v[110:113], v[126:129], v[82:97]
	s_cmp_gt_u32 s21, 61
	s_cbranch_scc1 .Lmla_skip_gb
	global_load_dwordx4 v[166:169], v194, vcc
	global_load_dwordx4 v[162:165], v195, vcc
	global_load_dwordx4 v[170:173], v196, vcc
	global_load_dwordx4 v[174:177], v192, s[100:101] offset:512
	global_load_dwordx4 v[178:181], v193, s[100:101] offset:512
; #define MFMA32(a, b, c) __builtin_amdgcn_mfma_f32_32x32x16_bf16((a), (b), (c), 0, 0, 0)
;     ...
;       for (int g = 0; g < NBAT; ++g) {
;         if (g + 1 < NBAT) {
;           const int t2n = (g + 1) / BPT, bn = (g + 1) % BPT;
; #pragma unroll
;           for (int i = 0; i < 4; ++i) kf[(g + 1) & 1][i] = *(const bf16x8*)(Ks + (32 * t2n + r) * KST + kcol_off + 16 * (4 * bn + i) + 8 * h);
;         }
;         __builtin_amdgcn_sched_barrier(0);
;         const int t2 = g / BPT, b = g % BPT;
; #pragma unroll
;         for (int i = 0; i < 4; ++i) st[t2] = MFMA32(kf[g & 1][i], qf[4 * b + i], st[t2]);
;         __builtin_amdgcn_sched_barrier(0);
;       }
;     }
;     bf16x8 vf[2][4];
; #pragma unroll
;     for (int dt = 0; dt < 4; ++dt) vf[0][dt] = *(const bf16x8*)(Vs + (32 * dt + r) * 72 + 8 * h);
;     if (MODE == 2) {
;       const float kb = (float)((kt0 + kt) * 64 + 4 * h);
; #pragma unroll
;       for (int t2 = 0; t2 < 2; ++t2)
; #pragma unroll
;         for (int e = 0; e < 16; ++e) {
;           float kp = kb + (float)(32 * t2 + (e & 3) + 8 * (e >> 2));
;           st[t2][e] *= __builtin_amdgcn_exp2f(dl * fabsf(qpos - kp));
;         }
;     } else if (MODE == 1) {
;       float ls = 0.f;
; #pragma unroll
;       for (int t2 = 0; t2 < 2; ++t2)
; #pragma unroll
;         for (int e = 0; e < 16; ++e) { float p = __builtin_amdgcn_exp2f(st[t2][e]); st[t2][e] = p; ls += p; }
;       l_run += ls;
;     } else {
;       float mx = st[0][0];
; #pragma unroll
;       for (int t2 = 0; t2 < 2; ++t2)
; #pragma unroll
;         for (int e = 0; e < 16; ++e) mx = fmaxf(mx, st[t2][e]);
;       mx = fmaxf(mx, shx(mx, 32));
;       float mnew = fmaxf(m_run, mx);
;       float alpha = __builtin_amdgcn_exp2f(m_run - mnew);
;       const bool changed = mnew > m_run;
;       m_run = mnew;
;       float ls = 0.f;
; #pragma unroll
;       for (int t2 = 0; t2 < 2; ++t2)
; #pragma unroll
;         for (int e = 0; e < 16; ++e) { float p = __builtin_amdgcn_exp2f(st[t2][e] - mnew); st[t2][e] = p; ls += p; }
;       l_run = l_run * alpha + ls;
;       if (__any(changed)) {
; #pragma unroll
;         for (int dt = 0; dt < 4; ++dt)
; #pragma unroll
;           for (int e = 0; e < 16; ++e) o[dt][e] *= alpha;
;       }
;     }
; #pragma unroll
;     for (int c = 0; c < 4; ++c) {
;       const int t2 = c >> 1, s2 = c & 1;
;       if (c + 1 < 4) {
; #pragma unroll
.Lmla_skip_gb:
	s_add_u32 vcc_lo, vcc_lo, s92
	s_addc_u32 vcc_hi, vcc_hi, s93
	s_add_u32 s100, s100, s30
	s_addc_u32 s101, s101, s31
	s_waitcnt lgkmcnt(8)
	v_mfma_f32_32x32x16_bf16 v[82:97], v[200:203], v[130:133], v[82:97]
	ds_read_b128 v[200:203], v220 offset:12800
	s_waitcnt lgkmcnt(8)
	v_mfma_f32_32x32x16_bf16 v[82:97], v[204:207], v[134:137], v[82:97]
	ds_read_b128 v[204:207], v220 offset:12832
	s_waitcnt lgkmcnt(8)
	v_mfma_f32_32x32x16_bf16 v[82:97], v[208:211], v[138:141], v[82:97]
	ds_read_b128 v[208:211], v220 offset:12864
	s_waitcnt lgkmcnt(6)
	v_mfma_f32_32x32x16_bf16 v[82:97], v[212:215], v[142:145], v[82:97]
	ds_read_b128 v[212:215], v220 offset:12896
	v_mfma_f32_32x32x16_bf16 v[82:97], v[216:219], v[146:149], v[82:97]
	ds_read_b128 v[216:219], v220 offset:12928
	v_mfma_f32_32x32x16_bf16 v[82:97], v[224:227], v[154:157], v[82:97]
	ds_read_b128 v[224:227], v220 offset:12960
	v_mfma_f32_32x32x16_bf16 v[82:97], v[230:233], v[150:153], v[82:97]
	ds_read_b128 v[230:233], v220 offset:12992
	v_mfma_f32_32x32x16_bf16 v[82:97], v[238:241], v[158:161], v[82:97]
	ds_read_b128 v[238:241], v220 offset:13024
	s_waitcnt lgkmcnt(7)
	v_mfma_f32_32x32x16_bf16 v[98:113], v[200:203], v[114:117], v[66:81]
	ds_read_b128 v[200:203], v220 offset:13056
	s_waitcnt lgkmcnt(7)
	v_mfma_f32_32x32x16_bf16 v[98:113], v[204:207], v[118:121], v[98:113]
	ds_read_b128 v[204:207], v220 offset:13088
	s_waitcnt lgkmcnt(7)
	v_mfma_f32_32x32x16_bf16 v[98:113], v[208:211], v[122:125], v[98:113]
	ds_read_b128 v[208:211], v220 offset:13120
	s_waitcnt lgkmcnt(7)
	v_mfma_f32_32x32x16_bf16 v[98:113], v[212:215], v[126:129], v[98:113]
	ds_read_b128 v[212:215], v220 offset:13152
	v_add_u32_e32 v220, v220, v189
	v_exp_f32_e32 v82, v82
	v_exp_f32_e32 v83, v83
	s_waitcnt lgkmcnt(7)
	v_mfma_f32_32x32x16_bf16 v[98:113], v[216:219], v[130:133], v[98:113]
	ds_read_b128 v[216:219], v220 offset:25600
	v_exp_f32_e32 v84, v84
	v_exp_f32_e32 v85, v85
	s_waitcnt lgkmcnt(7)
	v_mfma_f32_32x32x16_bf16 v[98:113], v[224:227], v[134:137], v[98:113]
	ds_read_b128 v[224:227], v220 offset:30208
	v_exp_f32_e32 v86, v86
	v_exp_f32_e32 v87, v87
	s_waitcnt lgkmcnt(7)
	v_mfma_f32_32x32x16_bf16 v[98:113], v[230:233], v[138:141], v[98:113]
	ds_read_b128 v[230:233], v220 offset:34816
	v_exp_f32_e32 v88, v88
	v_exp_f32_e32 v89, v89
	s_waitcnt lgkmcnt(7)
	v_mfma_f32_32x32x16_bf16 v[98:113], v[238:241], v[142:145], v[98:113]
	ds_read_b128 v[238:241], v220 offset:39424
	v_exp_f32_e32 v90, v90
	v_exp_f32_e32 v91, v91
	v_cvt_pk_bf16_f32 v242, v82, v83
	s_waitcnt lgkmcnt(7)
	v_mfma_f32_32x32x16_bf16 v[98:113], v[200:203], v[146:149], v[98:113]
	ds_read_b128 v[200:203], v220 offset:25632
	v_exp_f32_e32 v92, v92
	v_exp_f32_e32 v93, v93
	v_cvt_pk_bf16_f32 v243, v84, v85
	s_waitcnt lgkmcnt(7)
	v_mfma_f32_32x32x16_bf16 v[98:113], v[204:207], v[154:157], v[98:113]
	ds_read_b128 v[204:207], v220 offset:30240
	v_exp_f32_e32 v94, v94
	v_exp_f32_e32 v95, v95
	v_cvt_pk_bf16_f32 v244, v86, v87
	s_waitcnt lgkmcnt(7)
	v_mfma_f32_32x32x16_bf16 v[98:113], v[208:211], v[150:153], v[98:113]
	ds_read_b128 v[208:211], v220 offset:34848
	v_exp_f32_e32 v96, v96
	v_exp_f32_e32 v97, v97
	v_cvt_pk_bf16_f32 v245, v88, v89
	s_waitcnt lgkmcnt(7)
	v_mfma_f32_32x32x16_bf16 v[98:113], v[212:215], v[158:161], v[98:113]
	ds_read_b128 v[212:215], v220 offset:39456
	v_add_f32_e32 v246, v90, v91
	v_add_f32_e32 v246, v92, v246
	v_add_f32_e32 v246, v93, v246
	v_add_f32_e32 v246, v94, v246
	s_waitcnt lgkmcnt(7)
	v_mfma_f32_32x32x16_bf16 v[50:65], v[216:219], v[242:245], v[50:65]
	ds_read_b128 v[216:219], v220 offset:25664
	v_add_f32_e32 v246, v95, v246
	v_add_f32_e32 v246, v96, v246
	v_add_f32_e32 v246, v97, v246
	v_cvt_pk_bf16_f32 v90, v90, v91
	v_cvt_pk_bf16_f32 v91, v92, v93
	s_waitcnt lgkmcnt(7)
	v_mfma_f32_32x32x16_bf16 v[34:49], v[224:227], v[242:245], v[34:49]
	ds_read_b128 v[224:227], v220 offset:30272
	v_cvt_pk_bf16_f32 v92, v94, v95
	v_cvt_pk_bf16_f32 v93, v96, v97
	v_exp_f32_e32 v98, v98
	v_exp_f32_e32 v99, v99
	s_waitcnt lgkmcnt(7)
	v_mfma_f32_32x32x16_bf16 v[18:33], v[230:233], v[242:245], v[18:33]
	ds_read_b128 v[230:233], v220 offset:34880
	v_exp_f32_e32 v100, v100
	v_exp_f32_e32 v101, v101
	v_exp_f32_e32 v102, v102
	s_waitcnt lgkmcnt(7)
	v_mfma_f32_32x32x16_bf16 v[2:17], v[238:241], v[242:245], v[2:17]
	ds_read_b128 v[238:241], v220 offset:39488
	v_exp_f32_e32 v103, v103
	v_exp_f32_e32 v104, v104
	v_exp_f32_e32 v105, v105
	s_waitcnt lgkmcnt(7)
	v_mfma_f32_32x32x16_bf16 v[50:65], v[200:203], v[90:93], v[50:65]
	ds_read_b128 v[200:203], v220 offset:25696
	v_cvt_pk_bf16_f32 v94, v98, v99
	v_cvt_pk_bf16_f32 v95, v100, v101
	v_cvt_pk_bf16_f32 v96, v102, v103
	v_cvt_pk_bf16_f32 v97, v104, v105
	v_exp_f32_e32 v106, v106
	s_waitcnt lgkmcnt(7)
	v_mfma_f32_32x32x16_bf16 v[34:49], v[204:207], v[90:93], v[34:49]
	ds_read_b128 v[204:207], v220 offset:30304
	v_exp_f32_e32 v107, v107
	v_exp_f32_e32 v108, v108
	v_exp_f32_e32 v109, v109
	v_add_f32_e32 v246, v82, v246
	s_waitcnt lgkmcnt(7)
	v_mfma_f32_32x32x16_bf16 v[18:33], v[208:211], v[90:93], v[18:33]
	ds_read_b128 v[208:211], v220 offset:34912
	v_exp_f32_e32 v110, v110
	v_exp_f32_e32 v111, v111
	v_exp_f32_e32 v112, v112
	v_add_f32_e32 v246, v83, v246
	s_waitcnt lgkmcnt(7)
	v_mfma_f32_32x32x16_bf16 v[2:17], v[212:215], v[90:93], v[2:17]
	ds_read_b128 v[212:215], v220 offset:39520
	v_exp_f32_e32 v113, v113
	v_add_f32_e32 v247, v106, v107
	v_add_f32_e32 v247, v108, v247
	v_add_f32_e32 v246, v84, v246
	s_waitcnt lgkmcnt(7)
	v_mfma_f32_32x32x16_bf16 v[50:65], v[216:219], v[94:97], v[50:65]
	v_add_f32_e32 v247, v109, v247
	v_add_f32_e32 v247, v110, v247
	v_add_f32_e32 v247, v111, v247
	v_add_f32_e32 v247, v112, v247
	v_add_f32_e32 v247, v113, v247
	v_add_f32_e32 v246, v85, v246
	s_waitcnt lgkmcnt(6)
	v_mfma_f32_32x32x16_bf16 v[34:49], v[224:227], v[94:97], v[34:49]
	v_cvt_pk_bf16_f32 v242, v106, v107
	v_cvt_pk_bf16_f32 v243, v108, v109
	v_cvt_pk_bf16_f32 v244, v110, v111
	v_cvt_pk_bf16_f32 v245, v112, v113
	v_add_f32_e32 v247, v98, v247
	v_add_f32_e32 v246, v86, v246
	v_add_f32_e32 v247, v99, v247
	s_waitcnt lgkmcnt(5)
	v_mfma_f32_32x32x16_bf16 v[18:33], v[230:233], v[94:97], v[18:33]
	v_add_f32_e32 v247, v100, v247
	v_add_f32_e32 v246, v87, v246
	v_add_f32_e32 v247, v101, v247
	v_add_f32_e32 v246, v88, v246
	v_add_f32_e32 v247, v102, v247
	v_add_f32_e32 v246, v89, v246
	v_add_f32_e32 v247, v103, v247
	s_waitcnt lgkmcnt(4)
	v_mfma_f32_32x32x16_bf16 v[2:17], v[238:241], v[94:97], v[2:17]
	v_add_f32_e32 v247, v104, v247
	v_add_f32_e32 v247, v105, v247
	v_add_f32_e32 v246, v247, v246
	v_add_f32_e32 v185, v185, v246
	s_cmp_lg_u32 s22, 64
	s_waitcnt lgkmcnt(0)
	s_mov_b32 s21, s22
	s_barrier
	s_cbranch_scc1 .LBB0_590
